# K-loop priority raise + second K-tile prefetched into the idle fragment registers in the GEMM prologue
# speedup vs baseline: 1.0001x; 1.0001x over previous
.LBB0_146:
	s_ashr_i32 s8, s10, 3
	s_lshl_b32 s11, s8, 1
	s_and_b32 s9, s8, -16
	s_and_b32 s11, s11, 14
	s_or_b32 s9, s11, s9
	s_bfe_u32 s11, s8, 0x10003
	s_or_b32 s9, s9, s11
	s_cmp_lt_i32 s8, 0
	s_cselect_b32 s8, s9, s8
	s_lshl_b32 s9, s10, 5
	s_and_b32 s9, s9, 0xe0
	s_add_i32 s8, s8, s9
	s_ashr_i32 s9, s8, 31
	s_lshr_b32 s9, s9, 27
	s_add_i32 s9, s8, s9
	s_and_b32 s11, s9, 0xffffffe0
	s_sub_i32 s8, s8, s11
	s_ashr_i32 s11, s8, 31
	s_lshr_b32 s11, s11, 29
	s_add_i32 s11, s8, s11
	s_ashr_i32 s12, s11, 3
	s_lshl_b32 s9, s9, 5
	s_and_b32 s9, s9, 0xfffffc00
	s_lshl_b32 s11, s12, 8
	s_add_i32 s11, s11, s9
	s_lshl_b32 s9, s12, 10
	s_lshl_b32 s8, s8, 7
	v_mov_b32_e32 v6, v188
	s_sub_i32 s12, s8, s9
	s_mov_b32 s13, 0x30000
	v_ashrrev_i32_e32 v7, 3, v6
	v_lshlrev_b32_e32 v4, 4, v6
	v_and_b32_e32 v176, 0x70, v4
	v_add_u32_e32 v4, s12, v7
	v_ashrrev_i32_e32 v5, 31, v4
	v_add_u32_e32 v0, s11, v7
	v_lshlrev_b64 v[4:5], 11, v[4:5]
	v_ashrrev_i32_e32 v1, 31, v0
	v_lshl_add_u64 v[4:5], s[4:5], 0, v[4:5]
	v_xor_b32_e32 v8, v7, v6
	v_lshlrev_b64 v[0:1], 11, v[0:1]
	v_lshl_add_u64 v[178:179], v[4:5], 0, v[176:177]
	v_lshlrev_b32_e32 v4, 4, v8
	v_lshl_add_u64 v[2:3], s[2:3], 0, v[0:1]
	v_and_b32_e32 v4, 0x70, v4
	v_lshl_add_u64 v[2:3], v[2:3], 0, v[176:177]
	v_lshl_or_b32 v176, v7, 7, v4
	v_lshrrev_b32_e32 v4, 4, v6
	v_and_b32_e32 v15, 7, v6
	v_bitop3_b32 v20, v4, v15, 3 bitop3:0x6c
	v_add_co_u32_e32 v4, vcc, s13, v178
	v_lshlrev_b32_e32 v12, 7, v6
	s_nop 0
	v_addc_co_u32_e32 v5, vcc, 0, v179, vcc
	v_bfe_u32 v14, v6, 4, 2
	v_add_co_u32_e32 v6, vcc, s14, v178
	s_mov_b32 s8, 0x70000
	s_nop 0
	v_addc_co_u32_e32 v7, vcc, 0, v179, vcc
	global_load_dwordx4 v[8:11], v[4:5], off
	global_load_dwordx4 v[16:19], v[6:7], off
	v_add_co_u32_e32 v4, vcc, s31, v178
	v_and_b32_e32 v13, 0xffffc780, v12
	s_nop 0
	v_addc_co_u32_e32 v5, vcc, 0, v179, vcc
	v_add_co_u32_e32 v6, vcc, s8, v2
	s_mov_b32 s8, 0x60000
	s_nop 0
	v_addc_co_u32_e32 v7, vcc, 0, v3, vcc
	global_load_dwordx4 v[32:35], v[4:5], off
	global_load_dwordx4 v[40:43], v[6:7], off
	v_add_co_u32_e32 v4, vcc, s8, v2
	s_mov_b32 s8, 0x50000
	s_nop 0
	v_addc_co_u32_e32 v5, vcc, 0, v3, vcc
	v_add_co_u32_e32 v6, vcc, s8, v2
	v_and_b32_e32 v12, 0x2780, v12
	s_nop 0
	v_addc_co_u32_e32 v7, vcc, 0, v3, vcc
	global_load_dwordx4 v[60:63], v[4:5], off
	global_load_dwordx4 v[68:71], v[6:7], off
	v_add_co_u32_e32 v4, vcc, 0x40000, v2
	v_bitop3_b32 v14, v14, v15, 4 bitop3:0x36
	s_nop 0
	v_addc_co_u32_e32 v5, vcc, 0, v3, vcc
	v_add_co_u32_e32 v6, vcc, s13, v2
	v_lshl_or_b32 v0, v15, 4, v0
	s_nop 0
	v_addc_co_u32_e32 v7, vcc, 0, v3, vcc
	global_load_dwordx4 v[80:83], v[4:5], off
	global_load_dwordx4 v[88:91], v[6:7], off
	v_add_co_u32_e32 v4, vcc, s14, v2
	v_mov_b32_e32 v140, 0
	s_nop 0
	v_addc_co_u32_e32 v5, vcc, 0, v3, vcc
	v_add_co_u32_e32 v6, vcc, 0x10000, v2
	v_lshl_add_u64 v[180:181], s[34:35], 0, v[0:1]
	s_nop 0
	v_addc_co_u32_e32 v7, vcc, 0, v3, vcc
	global_load_dwordx4 v[104:107], v[4:5], off
	global_load_dwordx4 v[112:115], v[6:7], off
	global_load_dwordx4 v[56:59], v[178:179], off
	global_load_dwordx4 v[116:119], v[2:3], off
	v_lshlrev_b32_e32 v2, 4, v20
	v_or_b32_e32 v185, v13, v2
	v_or_b32_e32 v184, v12, v2
	v_lshlrev_b32_e32 v2, 4, v14
	v_or_b32_e32 v183, v13, v2
	v_or_b32_e32 v182, v12, v2
	s_mov_b64 s[8:9], 0
	v_mov_b32_e32 v141, v140
	v_mov_b32_e32 v142, v140
	v_mov_b32_e32 v143, v140
	v_mov_b32_e32 v0, v140
	v_mov_b32_e32 v1, v140
	v_mov_b32_e32 v2, v140
	v_mov_b32_e32 v3, v140
	v_mov_b32_e32 v4, v140
	v_mov_b32_e32 v5, v140
	v_mov_b32_e32 v6, v140
	v_mov_b32_e32 v7, v140
	v_mov_b32_e32 v12, v140
	v_mov_b32_e32 v13, v140
	v_mov_b32_e32 v14, v140
	v_mov_b32_e32 v15, v140
	v_mov_b32_e32 v20, v140
	v_mov_b32_e32 v21, v140
	v_mov_b32_e32 v22, v140
	v_mov_b32_e32 v23, v140
	v_mov_b32_e32 v24, v140
	v_mov_b32_e32 v25, v140
	v_mov_b32_e32 v26, v140
	v_mov_b32_e32 v27, v140
	v_mov_b32_e32 v28, v140
	v_mov_b32_e32 v29, v140
	v_mov_b32_e32 v30, v140
	v_mov_b32_e32 v31, v140
	v_mov_b32_e32 v36, v140
	v_mov_b32_e32 v37, v140
	v_mov_b32_e32 v38, v140
	v_mov_b32_e32 v39, v140
	v_mov_b32_e32 v44, v140
	v_mov_b32_e32 v45, v140
	v_mov_b32_e32 v46, v140
	v_mov_b32_e32 v47, v140
	v_mov_b32_e32 v48, v140
	v_mov_b32_e32 v49, v140
	v_mov_b32_e32 v50, v140
	v_mov_b32_e32 v51, v140
	v_mov_b32_e32 v52, v140
	v_mov_b32_e32 v53, v140
	v_mov_b32_e32 v54, v140
	v_mov_b32_e32 v55, v140
	v_mov_b32_e32 v64, v140
	v_mov_b32_e32 v65, v140
	v_mov_b32_e32 v66, v140
	v_mov_b32_e32 v67, v140
	v_mov_b32_e32 v72, v140
	v_mov_b32_e32 v73, v140
	v_mov_b32_e32 v74, v140
	v_mov_b32_e32 v75, v140
	v_mov_b32_e32 v76, v140
	v_mov_b32_e32 v77, v140
	v_mov_b32_e32 v78, v140
	v_mov_b32_e32 v79, v140
	v_mov_b32_e32 v84, v140
	v_mov_b32_e32 v85, v140
	v_mov_b32_e32 v86, v140
	v_mov_b32_e32 v87, v140
	v_mov_b32_e32 v92, v140
	v_mov_b32_e32 v93, v140
	v_mov_b32_e32 v94, v140
	v_mov_b32_e32 v95, v140
	v_mov_b32_e32 v96, v140
	v_mov_b32_e32 v97, v140
	v_mov_b32_e32 v98, v140
	v_mov_b32_e32 v99, v140
	v_mov_b32_e32 v100, v140
	v_mov_b32_e32 v101, v140
	v_mov_b32_e32 v102, v140
	v_mov_b32_e32 v103, v140
	v_mov_b32_e32 v108, v140
	v_mov_b32_e32 v109, v140
	v_mov_b32_e32 v110, v140
	v_mov_b32_e32 v111, v140
	v_mov_b32_e32 v120, v140
	v_mov_b32_e32 v121, v140
	v_mov_b32_e32 v122, v140
	v_mov_b32_e32 v123, v140
	v_mov_b32_e32 v124, v140
	v_mov_b32_e32 v125, v140
	v_mov_b32_e32 v126, v140
	v_mov_b32_e32 v127, v140
	v_mov_b32_e32 v128, v140
	v_mov_b32_e32 v129, v140
	v_mov_b32_e32 v130, v140
	v_mov_b32_e32 v131, v140
	v_mov_b32_e32 v132, v140
	v_mov_b32_e32 v133, v140
	v_mov_b32_e32 v134, v140
	v_mov_b32_e32 v135, v140
	v_mov_b32_e32 v136, v140
	v_mov_b32_e32 v137, v140
	v_mov_b32_e32 v138, v140
	v_mov_b32_e32 v139, v140
	v_mov_b32_e32 v144, v140
	v_mov_b32_e32 v145, v140
	v_mov_b32_e32 v146, v140
	v_mov_b32_e32 v147, v140
	v_mov_b32_e32 v148, v140
	v_mov_b32_e32 v149, v140
	v_mov_b32_e32 v150, v140
	v_mov_b32_e32 v151, v140
	v_mov_b32_e32 v152, v140
	v_mov_b32_e32 v153, v140
	v_mov_b32_e32 v154, v140
	v_mov_b32_e32 v155, v140
	v_mov_b32_e32 v156, v140
	v_mov_b32_e32 v157, v140
	v_mov_b32_e32 v158, v140
	v_mov_b32_e32 v159, v140
	v_mov_b32_e32 v160, v140
	v_mov_b32_e32 v161, v140
	v_mov_b32_e32 v162, v140
	v_mov_b32_e32 v163, v140
	v_mov_b32_e32 v164, v140
	v_mov_b32_e32 v165, v140
	v_mov_b32_e32 v166, v140
	v_mov_b32_e32 v167, v140
	v_mov_b32_e32 v168, v140
	v_mov_b32_e32 v169, v140
	v_mov_b32_e32 v170, v140
	v_mov_b32_e32 v171, v140
	v_mov_b32_e32 v172, v140
	v_mov_b32_e32 v173, v140
	v_mov_b32_e32 v174, v140
	v_mov_b32_e32 v175, v140
	s_setprio 2
	v_readlane_b32 s98, v253, 3
	v_readlane_b32 s99, v253, 4
	v_and_b32_e32 v224, 15, v188
	v_bfe_u32 v225, v188, 4, 2
	v_lshrrev_b32_e32 v226, 2, v224
	v_sub_u32_e32 v226, 0, v226
	v_and_b32_e32 v226, 3, v226
	v_xor_b32_e32 v225, v225, v226
	v_lshlrev_b32_e32 v225, 4, v225
	v_lshl_or_b32 v225, v224, 6, v225
	v_bfe_u32 v226, v188, 7, 1
	v_lshl_or_b32 v185, v226, 13, v225
	v_bfe_u32 v226, v188, 6, 1
	v_lshl_or_b32 v184, v226, 12, v225
	v_add_u32_e32 v184, 0x4000, v184
	v_lshrrev_b32_e32 v224, 3, v188
	v_bfe_u32 v225, v188, 2, 1
	v_lshrrev_b32_e32 v226, 2, v224
	v_sub_u32_e32 v226, 0, v226
	v_and_b32_e32 v226, 3, v226
	v_and_b32_e32 v227, 3, v188
	v_xor_b32_e32 v226, v227, v226
	v_lshlrev_b32_e32 v226, 4, v226
	v_xor_b32_e32 v224, v224, v225
	v_lshl_or_b32 v226, v224, 6, v226
	v_mul_u32_u24_e32 v225, 0x6000, v225
	v_add_u32_e32 v183, v225, v226
	s_mov_b32 m0, 0
	s_sub_u32 vcc_lo, s8, s98
	v_add_u32_e32 v186, vcc_lo, v178
	v_add_u32_e32 v187, vcc_lo, v180
	v_add_u32_e32 v190, s26, v187
	global_load_dwordx4 v[190:193], v190, s[98:99] offset:128
	v_add_u32_e32 v194, s27, v187
	global_load_dwordx4 v[194:197], v194, s[98:99] offset:128
	v_add_u32_e32 v198, s20, v187
	global_load_dwordx4 v[198:201], v198, s[98:99] offset:128
	v_add_u32_e32 v204, s21, v187
	global_load_dwordx4 v[204:207], v204, s[98:99] offset:128
	v_add_u32_e32 v208, s56, v187
	global_load_dwordx4 v[208:211], v208, s[98:99] offset:128
	v_add_u32_e32 v212, s57, v187
	global_load_dwordx4 v[212:215], v212, s[98:99] offset:128
	v_add_u32_e32 v216, s24, v187
	global_load_dwordx4 v[216:219], v216, s[98:99] offset:128
	v_add_u32_e32 v220, s96, v187
	global_load_dwordx4 v[220:223], v220, s[98:99] offset:128
	v_mov_b32_e32 v224, v186
	global_load_dwordx4 v[224:227], v224, s[98:99] offset:128
	v_add_u32_e32 v228, s31, v186
	global_load_dwordx4 v[228:231], v228, s[98:99] offset:128
	v_add_u32_e32 v232, s14, v186
	global_load_dwordx4 v[232:235], v232, s[98:99] offset:128
	v_add_u32_e32 v236, s13, v186
	global_load_dwordx4 v[236:239], v236, s[98:99] offset:128
	s_barrier
	s_waitcnt vmcnt(12)
	ds_write_b128 v183, v[116:119]
	ds_write_b128 v183, v[112:115] offset:2048
	ds_write_b128 v183, v[104:107] offset:4096
	ds_write_b128 v183, v[88:91] offset:6144
	ds_write_b128 v183, v[80:83] offset:8192
	ds_write_b128 v183, v[68:71] offset:10240
	ds_write_b128 v183, v[60:63] offset:12288
	ds_write_b128 v183, v[40:43] offset:14336
	ds_write_b128 v183, v[56:59] offset:16384
	ds_write_b128 v183, v[32:35] offset:18432
	ds_write_b128 v183, v[16:19] offset:20480
	ds_write_b128 v183, v[8:11] offset:22528
	v_cmp_gt_u32_e32 vcc, 0x6000, v183
	v_add_u32_e32 v182, 0xc000, v183
	v_add_u32_e32 v183, 0xffffa000, v183
	s_nop 0
	v_cndmask_b32_e32 v183, v183, v182, vcc
	s_waitcnt vmcnt(0)
	v_mov_b64_e32 v[116:117], v[190:191]
	v_mov_b64_e32 v[118:119], v[192:193]
	v_mov_b64_e32 v[112:113], v[194:195]
	v_mov_b64_e32 v[114:115], v[196:197]
	v_mov_b64_e32 v[104:105], v[198:199]
	v_mov_b64_e32 v[106:107], v[200:201]
	v_mov_b64_e32 v[88:89], v[204:205]
	v_mov_b64_e32 v[90:91], v[206:207]
	v_mov_b64_e32 v[80:81], v[208:209]
	v_mov_b64_e32 v[82:83], v[210:211]
	v_mov_b64_e32 v[68:69], v[212:213]
	v_mov_b64_e32 v[70:71], v[214:215]
	v_mov_b64_e32 v[60:61], v[216:217]
	v_mov_b64_e32 v[62:63], v[218:219]
	v_mov_b64_e32 v[40:41], v[220:221]
	v_mov_b64_e32 v[42:43], v[222:223]
	v_mov_b64_e32 v[56:57], v[224:225]
	v_mov_b64_e32 v[58:59], v[226:227]
	v_mov_b64_e32 v[32:33], v[228:229]
	v_mov_b64_e32 v[34:35], v[230:231]
	v_mov_b64_e32 v[16:17], v[232:233]
	v_mov_b64_e32 v[18:19], v[234:235]
	v_mov_b64_e32 v[8:9], v[236:237]
	v_mov_b64_e32 v[10:11], v[238:239]
	s_add_u32 s8, s8, 0x80
	s_addc_u32 s9, s9, 0

.LBB0_398:
	s_andn2_b64 vcc, exec, s[0:1]
	s_cbranch_vccnz .LBB0_418
	s_add_i32 s0, s7, 0xfffffdc0
	s_and_b32 s1, s7, 7
	s_lshr_b32 s0, s0, 3
	s_mul_i32 s1, s1, 48
	s_add_i32 s1, s1, s0
	s_and_b32 s0, s1, 0xffff
	s_mul_i32 s0, s0, 0xaaab
	s_lshr_b32 s8, s0, 20
	s_mul_i32 s9, s8, 0xffffffe8
	s_add_i32 s1, s9, s1
	s_mul_i32 s9, s1, 0x2aab
	s_lshr_b32 s30, s9, 31
	s_lshr_b32 s9, s9, 16
	s_lshr_b32 s0, s0, 21
	s_add_i32 s9, s9, s30
	s_sext_i32_i16 s9, s9
	s_lshl_b32 s30, s0, 1
	s_add_i32 s30, s30, s9
	s_lshl_b32 s0, s0, 10
	s_lshl_b32 s9, s9, 8
	v_mov_b32_e32 v8, v188
	s_sub_i32 s8, s8, s30
	s_add_i32 s9, s9, s0
	s_mul_i32 s8, s8, 6
	v_ashrrev_i32_e32 v9, 3, v8
	v_add_u32_e32 v4, s9, v9
	s_movk_i32 s30, 0x300
	s_add_i32 s8, s8, s1
	v_mad_i64_i32 v[0:1], s[0:1], v4, s30, 0
	v_readlane_b32 s0, v255, 49
	v_readlane_b32 s1, v255, 50
	s_lshl_b32 s8, s8, 7
	v_add_u32_e32 v10, s8, v9
	v_mov_b64_e32 v[2:3], s[0:1]
	v_mad_i64_i32 v[2:3], s[0:1], v4, s30, v[2:3]
	v_lshlrev_b32_e32 v4, 4, v8
	v_and_b32_e32 v176, 0x70, v4
	v_mad_i64_i32 v[4:5], s[0:1], v10, s30, 0
	v_readlane_b32 s0, v255, 51
	v_readlane_b32 s1, v255, 52
	v_lshl_add_u64 v[2:3], v[2:3], 0, v[176:177]
	v_lshlrev_b32_e32 v12, 7, v8
	v_mov_b64_e32 v[6:7], s[0:1]
	v_mad_i64_i32 v[6:7], s[0:1], v10, s30, v[6:7]
	v_xor_b32_e32 v10, v9, v8
	v_lshlrev_b32_e32 v10, 4, v10
	v_lshl_add_u64 v[6:7], v[6:7], 0, v[176:177]
	v_and_b32_e32 v10, 0x70, v10
	v_lshl_or_b32 v176, v9, 7, v10
	v_lshrrev_b32_e32 v9, 4, v8
	v_bfe_u32 v14, v8, 4, 2
	v_and_b32_e32 v15, 7, v8
	v_add_co_u32_e32 v8, vcc, s77, v6
	v_bitop3_b32 v16, v9, v15, 3 bitop3:0x6c
	s_nop 0
	v_addc_co_u32_e32 v9, vcc, 0, v7, vcc
	v_add_co_u32_e32 v10, vcc, s28, v6
	s_mov_b32 s0, 0x2a000
	s_nop 0
	v_addc_co_u32_e32 v11, vcc, 0, v7, vcc
	global_load_dwordx4 v[68:71], v[8:9], off
	global_load_dwordx4 v[72:75], v[10:11], off
	v_add_co_u32_e32 v8, vcc, s54, v6
	v_and_b32_e32 v13, 0xffffc780, v12
	s_nop 0
	v_addc_co_u32_e32 v9, vcc, 0, v7, vcc
	v_add_co_u32_e32 v10, vcc, s0, v2
	s_mov_b32 s0, 0x24000
	s_nop 0
	v_addc_co_u32_e32 v11, vcc, 0, v3, vcc
	global_load_dwordx4 v[88:91], v[8:9], off
	global_load_dwordx4 v[96:99], v[10:11], off
	v_add_co_u32_e32 v8, vcc, s0, v2
	s_mov_b32 s0, 0x1e000
	s_nop 0
	v_addc_co_u32_e32 v9, vcc, 0, v3, vcc
	v_add_co_u32_e32 v10, vcc, s0, v2
	s_mov_b32 s0, 0x18000
	s_nop 0
	v_addc_co_u32_e32 v11, vcc, 0, v3, vcc
	global_load_dwordx4 v[108:111], v[8:9], off
	global_load_dwordx4 v[120:123], v[10:11], off
	v_add_co_u32_e32 v8, vcc, s0, v2
	v_and_b32_e32 v12, 0x2780, v12
	s_nop 0
	v_addc_co_u32_e32 v9, vcc, 0, v3, vcc
	v_add_co_u32_e32 v10, vcc, s77, v2
	v_bitop3_b32 v14, v14, v15, 4 bitop3:0x36
	s_nop 0
	v_addc_co_u32_e32 v11, vcc, 0, v3, vcc
	global_load_dwordx4 v[132:135], v[8:9], off
	global_load_dwordx4 v[136:139], v[10:11], off
	v_add_co_u32_e32 v8, vcc, s28, v2
	v_mov_b32_e32 v112, 0
	s_nop 0
	v_addc_co_u32_e32 v9, vcc, 0, v3, vcc
	v_add_co_u32_e32 v10, vcc, s54, v2
	s_mov_b64 s[0:1], 0
	s_nop 0
	v_addc_co_u32_e32 v11, vcc, 0, v3, vcc
	global_load_dwordx4 v[152:155], v[8:9], off
	global_load_dwordx4 v[160:163], v[10:11], off
	global_load_dwordx4 v[148:151], v[6:7], off
	global_load_dwordx4 v[168:171], v[2:3], off
	v_lshlrev_b32_e32 v2, 4, v16
	v_or_b32_e32 v185, v13, v2
	v_or_b32_e32 v184, v12, v2
	v_lshlrev_b32_e32 v2, 4, v14
	v_or_b32_e32 v183, v13, v2
	v_or_b32_e32 v182, v12, v2
	v_lshlrev_b32_e32 v2, 4, v15
	v_or_b32_e32 v0, v0, v2
	v_or_b32_e32 v4, v4, v2
	v_lshl_add_u64 v[178:179], s[34:35], 0, v[0:1]
	v_lshl_add_u64 v[180:181], s[84:85], 0, v[4:5]
	v_mov_b32_e32 v113, v112
	v_mov_b32_e32 v114, v112
	v_mov_b32_e32 v115, v112
	v_mov_b32_e32 v0, v112
	v_mov_b32_e32 v1, v112
	v_mov_b32_e32 v2, v112
	v_mov_b32_e32 v3, v112
	v_mov_b32_e32 v4, v112
	v_mov_b32_e32 v5, v112
	v_mov_b32_e32 v6, v112
	v_mov_b32_e32 v7, v112
	v_mov_b32_e32 v8, v112
	v_mov_b32_e32 v9, v112
	v_mov_b32_e32 v10, v112
	v_mov_b32_e32 v11, v112
	v_mov_b32_e32 v12, v112
	v_mov_b32_e32 v13, v112
	v_mov_b32_e32 v14, v112
	v_mov_b32_e32 v15, v112
	v_mov_b32_e32 v16, v112
	v_mov_b32_e32 v17, v112
	v_mov_b32_e32 v18, v112
	v_mov_b32_e32 v19, v112
	v_mov_b32_e32 v20, v112
	v_mov_b32_e32 v21, v112
	v_mov_b32_e32 v22, v112
	v_mov_b32_e32 v23, v112
	v_mov_b32_e32 v24, v112
	v_mov_b32_e32 v25, v112
	v_mov_b32_e32 v26, v112
	v_mov_b32_e32 v27, v112
	v_mov_b32_e32 v28, v112
	v_mov_b32_e32 v29, v112
	v_mov_b32_e32 v30, v112
	v_mov_b32_e32 v31, v112
	v_mov_b32_e32 v32, v112
	v_mov_b32_e32 v33, v112
	v_mov_b32_e32 v34, v112
	v_mov_b32_e32 v35, v112
	v_mov_b32_e32 v36, v112
	v_mov_b32_e32 v37, v112
	v_mov_b32_e32 v38, v112
	v_mov_b32_e32 v39, v112
	v_mov_b32_e32 v40, v112
	v_mov_b32_e32 v41, v112
	v_mov_b32_e32 v42, v112
	v_mov_b32_e32 v43, v112
	v_mov_b32_e32 v44, v112
	v_mov_b32_e32 v45, v112
	v_mov_b32_e32 v46, v112
	v_mov_b32_e32 v47, v112
	v_mov_b32_e32 v48, v112
	v_mov_b32_e32 v49, v112
	v_mov_b32_e32 v50, v112
	v_mov_b32_e32 v51, v112
	v_mov_b32_e32 v52, v112
	v_mov_b32_e32 v53, v112
	v_mov_b32_e32 v54, v112
	v_mov_b32_e32 v55, v112
	v_mov_b32_e32 v56, v112
	v_mov_b32_e32 v57, v112
	v_mov_b32_e32 v58, v112
	v_mov_b32_e32 v59, v112
	v_mov_b32_e32 v60, v112
	v_mov_b32_e32 v61, v112
	v_mov_b32_e32 v62, v112
	v_mov_b32_e32 v63, v112
	v_mov_b32_e32 v64, v112
	v_mov_b32_e32 v65, v112
	v_mov_b32_e32 v66, v112
	v_mov_b32_e32 v67, v112
	v_mov_b32_e32 v76, v112
	v_mov_b32_e32 v77, v112
	v_mov_b32_e32 v78, v112
	v_mov_b32_e32 v79, v112
	v_mov_b32_e32 v80, v112
	v_mov_b32_e32 v81, v112
	v_mov_b32_e32 v82, v112
	v_mov_b32_e32 v83, v112
	v_mov_b32_e32 v84, v112
	v_mov_b32_e32 v85, v112
	v_mov_b32_e32 v86, v112
	v_mov_b32_e32 v87, v112
	v_mov_b32_e32 v92, v112
	v_mov_b32_e32 v93, v112
	v_mov_b32_e32 v94, v112
	v_mov_b32_e32 v95, v112
	v_mov_b32_e32 v100, v112
	v_mov_b32_e32 v101, v112
	v_mov_b32_e32 v102, v112
	v_mov_b32_e32 v103, v112
	v_mov_b32_e32 v104, v112
	v_mov_b32_e32 v105, v112
	v_mov_b32_e32 v106, v112
	v_mov_b32_e32 v107, v112
	v_mov_b32_e32 v116, v112
	v_mov_b32_e32 v117, v112
	v_mov_b32_e32 v118, v112
	v_mov_b32_e32 v119, v112
	v_mov_b32_e32 v124, v112
	v_mov_b32_e32 v125, v112
	v_mov_b32_e32 v126, v112
	v_mov_b32_e32 v127, v112
	v_mov_b32_e32 v128, v112
	v_mov_b32_e32 v129, v112
	v_mov_b32_e32 v130, v112
	v_mov_b32_e32 v131, v112
	v_mov_b32_e32 v140, v112
	v_mov_b32_e32 v141, v112
	v_mov_b32_e32 v142, v112
	v_mov_b32_e32 v143, v112
	v_mov_b32_e32 v144, v112
	v_mov_b32_e32 v145, v112
	v_mov_b32_e32 v146, v112
	v_mov_b32_e32 v147, v112
	v_mov_b32_e32 v156, v112
	v_mov_b32_e32 v157, v112
	v_mov_b32_e32 v158, v112
	v_mov_b32_e32 v159, v112
	v_mov_b32_e32 v164, v112
	v_mov_b32_e32 v165, v112
	v_mov_b32_e32 v166, v112
	v_mov_b32_e32 v167, v112
	v_mov_b32_e32 v172, v112
	v_mov_b32_e32 v173, v112
	v_mov_b32_e32 v174, v112
	v_mov_b32_e32 v175, v112
	s_setprio 2
	v_readlane_b32 s98, v253, 3
	v_readlane_b32 s99, v253, 4
	v_and_b32_e32 v224, 15, v188
	v_bfe_u32 v225, v188, 4, 2
	v_lshrrev_b32_e32 v226, 2, v224
	v_sub_u32_e32 v226, 0, v226
	v_and_b32_e32 v226, 3, v226
	v_xor_b32_e32 v225, v225, v226
	v_lshlrev_b32_e32 v225, 4, v225
	v_lshl_or_b32 v225, v224, 6, v225
	v_bfe_u32 v226, v188, 7, 1
	v_lshl_or_b32 v185, v226, 13, v225
	v_bfe_u32 v226, v188, 6, 1
	v_lshl_or_b32 v184, v226, 12, v225
	v_add_u32_e32 v184, 0x4000, v184
	v_lshrrev_b32_e32 v224, 3, v188
	v_bfe_u32 v225, v188, 2, 1
	v_lshrrev_b32_e32 v226, 2, v224
	v_sub_u32_e32 v226, 0, v226
	v_and_b32_e32 v226, 3, v226
	v_and_b32_e32 v227, 3, v188
	v_xor_b32_e32 v226, v227, v226
	v_lshlrev_b32_e32 v226, 4, v226
	v_xor_b32_e32 v224, v224, v225
	v_lshl_or_b32 v226, v224, 6, v226
	v_mul_u32_u24_e32 v225, 0x6000, v225
	v_add_u32_e32 v183, v225, v226
	s_mov_b32 m0, 0
	s_sub_u32 vcc_lo, s0, s98
	v_add_u32_e32 v186, vcc_lo, v178
	v_add_u32_e32 v187, vcc_lo, v180
	v_add_u32_e32 v190, 0xa700000, v186
	global_load_dwordx4 v[190:193], v190, s[98:99] offset:128
	v_add_u32_e32 v194, 0xa706000, v186
	global_load_dwordx4 v[194:197], v194, s[98:99] offset:128
	v_add_u32_e32 v198, 0xa70c000, v186
	global_load_dwordx4 v[198:201], v198, s[98:99] offset:128
	v_add_u32_e32 v204, 0xa712000, v186
	global_load_dwordx4 v[204:207], v204, s[98:99] offset:128
	v_add_u32_e32 v208, 0xa718000, v186
	global_load_dwordx4 v[208:211], v208, s[98:99] offset:128
	v_add_u32_e32 v212, 0xa71e000, v186
	global_load_dwordx4 v[212:215], v212, s[98:99] offset:128
	v_add_u32_e32 v216, 0xa724000, v186
	global_load_dwordx4 v[216:219], v216, s[98:99] offset:128
	v_add_u32_e32 v220, 0xa72a000, v186
	global_load_dwordx4 v[220:223], v220, s[98:99] offset:128
	v_add_u32_e32 v224, 0x1f00000, v187
	global_load_dwordx4 v[224:227], v224, s[98:99] offset:128
	v_add_u32_e32 v228, 0x1f06000, v187
	global_load_dwordx4 v[228:231], v228, s[98:99] offset:128
	v_add_u32_e32 v232, 0x1f0c000, v187
	global_load_dwordx4 v[232:235], v232, s[98:99] offset:128
	v_add_u32_e32 v236, 0x1f12000, v187
	global_load_dwordx4 v[236:239], v236, s[98:99] offset:128
	s_barrier
	s_waitcnt vmcnt(12)
	ds_write_b128 v183, v[168:171]
	ds_write_b128 v183, v[160:163] offset:2048
	ds_write_b128 v183, v[152:155] offset:4096
	ds_write_b128 v183, v[136:139] offset:6144
	ds_write_b128 v183, v[132:135] offset:8192
	ds_write_b128 v183, v[120:123] offset:10240
	ds_write_b128 v183, v[108:111] offset:12288
	ds_write_b128 v183, v[96:99] offset:14336
	ds_write_b128 v183, v[148:151] offset:16384
	ds_write_b128 v183, v[88:91] offset:18432
	ds_write_b128 v183, v[72:75] offset:20480
	ds_write_b128 v183, v[68:71] offset:22528
	v_cmp_gt_u32_e32 vcc, 0x6000, v183
	v_add_u32_e32 v182, 0xc000, v183
	v_add_u32_e32 v183, 0xffffa000, v183
	s_nop 0
	v_cndmask_b32_e32 v183, v183, v182, vcc
	s_waitcnt vmcnt(0)
	v_mov_b64_e32 v[168:169], v[190:191]
	v_mov_b64_e32 v[170:171], v[192:193]
	v_mov_b64_e32 v[160:161], v[194:195]
	v_mov_b64_e32 v[162:163], v[196:197]
	v_mov_b64_e32 v[152:153], v[198:199]
	v_mov_b64_e32 v[154:155], v[200:201]
	v_mov_b64_e32 v[136:137], v[204:205]
	v_mov_b64_e32 v[138:139], v[206:207]
	v_mov_b64_e32 v[132:133], v[208:209]
	v_mov_b64_e32 v[134:135], v[210:211]
	v_mov_b64_e32 v[120:121], v[212:213]
	v_mov_b64_e32 v[122:123], v[214:215]
	v_mov_b64_e32 v[108:109], v[216:217]
	v_mov_b64_e32 v[110:111], v[218:219]
	v_mov_b64_e32 v[96:97], v[220:221]
	v_mov_b64_e32 v[98:99], v[222:223]
	v_mov_b64_e32 v[148:149], v[224:225]
	v_mov_b64_e32 v[150:151], v[226:227]
	v_mov_b64_e32 v[88:89], v[228:229]
	v_mov_b64_e32 v[90:91], v[230:231]
	v_mov_b64_e32 v[72:73], v[232:233]
	v_mov_b64_e32 v[74:75], v[234:235]
	v_mov_b64_e32 v[68:69], v[236:237]
	v_mov_b64_e32 v[70:71], v[238:239]
	s_add_u32 s0, s0, 0x80
	s_addc_u32 s1, s1, 0

.LBB0_422:
	s_lshl_b32 s42, s42, 1
	s_ashr_i32 s9, s9, 5
	s_sub_i32 s42, s42, s43
	s_add_i32 s9, s9, s42
	s_lshl_b32 s9, s9, 3
	s_add_i32 s9, s9, s1
	s_lshl_b32 s94, s9, 7
	s_and_b64 s[42:43], s[92:93], exec
	s_mov_b32 s1, 0x2400000
	s_cselect_b32 s1, s1, 0x2200000
	s_add_u32 s42, s36, s1
	s_addc_u32 s43, s6, 0
	s_and_b32 s95, s0, 1
	s_bitcmp1_b32 s0, 0
	s_cselect_b64 s[0:1], -1, 0
	s_cmp_eq_u32 s95, 0
	s_cbranch_scc1 .LBB0_426
	v_mov_b32_e32 v6, v188
	s_mov_b32 s95, 0x8000
	v_ashrrev_i32_e32 v7, 3, v6
	v_lshlrev_b32_e32 v4, 4, v6
	v_and_b32_e32 v176, 0x70, v4
	v_add_u32_e32 v4, s94, v7
	v_ashrrev_i32_e32 v5, 31, v4
	v_add_u32_e32 v0, s8, v7
	v_lshlrev_b64 v[4:5], 9, v[4:5]
	v_ashrrev_i32_e32 v1, 31, v0
	v_lshl_add_u64 v[4:5], s[42:43], 0, v[4:5]
	v_xor_b32_e32 v8, v7, v6
	v_lshlrev_b64 v[0:1], 9, v[0:1]
	v_lshl_add_u64 v[178:179], v[4:5], 0, v[176:177]
	v_lshlrev_b32_e32 v4, 4, v8
	v_lshl_add_u64 v[2:3], s[46:47], 0, v[0:1]
	v_and_b32_e32 v4, 0x70, v4
	v_lshl_add_u64 v[2:3], v[2:3], 0, v[176:177]
	v_lshl_or_b32 v176, v7, 7, v4
	v_lshrrev_b32_e32 v4, 4, v6
	v_and_b32_e32 v11, 7, v6
	v_bitop3_b32 v12, v4, v11, 3 bitop3:0x6c
	v_add_co_u32_e32 v4, vcc, s28, v178
	v_lshlrev_b32_e32 v8, 7, v6
	s_nop 0
	v_addc_co_u32_e32 v5, vcc, 0, v179, vcc
	v_bfe_u32 v10, v6, 4, 2
	v_add_co_u32_e32 v6, vcc, s95, v178
	s_movk_i32 s16, 0x4000
	s_nop 0
	v_addc_co_u32_e32 v7, vcc, 0, v179, vcc
	global_load_dwordx4 v[20:23], v[4:5], off
	global_load_dwordx4 v[24:27], v[6:7], off
	v_add_co_u32_e32 v4, vcc, s16, v178
	s_mov_b32 s15, 0x1c000
	s_nop 0
	v_addc_co_u32_e32 v5, vcc, 0, v179, vcc
	v_add_co_u32_e32 v6, vcc, s15, v2
	s_mov_b32 s15, 0x18000
	s_nop 0
	v_addc_co_u32_e32 v7, vcc, 0, v3, vcc
	global_load_dwordx4 v[40:43], v[4:5], off
	global_load_dwordx4 v[48:51], v[6:7], off
	v_add_co_u32_e32 v4, vcc, s15, v2
	s_mov_b32 s15, 0x14000
	s_nop 0
	v_addc_co_u32_e32 v5, vcc, 0, v3, vcc
	v_add_co_u32_e32 v6, vcc, s15, v2
	v_and_b32_e32 v9, 0xffffc780, v8
	s_nop 0
	v_addc_co_u32_e32 v7, vcc, 0, v3, vcc
	global_load_dwordx4 v[68:71], v[4:5], off
	global_load_dwordx4 v[72:75], v[6:7], off
	v_add_co_u32_e32 v4, vcc, s14, v2
	v_and_b32_e32 v8, 0x2780, v8
	s_nop 0
	v_addc_co_u32_e32 v5, vcc, 0, v3, vcc
	v_add_co_u32_e32 v6, vcc, s28, v2
	v_bitop3_b32 v10, v10, v11, 4 bitop3:0x36
	s_nop 0
	v_addc_co_u32_e32 v7, vcc, 0, v3, vcc
	global_load_dwordx4 v[84:87], v[4:5], off
	global_load_dwordx4 v[92:95], v[6:7], off
	v_add_co_u32_e32 v4, vcc, s95, v2
	v_lshl_or_b32 v0, v11, 4, v0
	s_nop 0
	v_addc_co_u32_e32 v5, vcc, 0, v3, vcc
	v_add_co_u32_e32 v6, vcc, s16, v2
	v_mov_b32_e32 v140, 0
	s_nop 0
	v_addc_co_u32_e32 v7, vcc, 0, v3, vcc
	global_load_dwordx4 v[104:107], v[4:5], off
	global_load_dwordx4 v[112:115], v[6:7], off
	global_load_dwordx4 v[56:59], v[178:179], off
	global_load_dwordx4 v[116:119], v[2:3], off
	v_lshlrev_b32_e32 v2, 4, v12
	v_or_b32_e32 v185, v9, v2
	v_or_b32_e32 v184, v8, v2
	v_lshlrev_b32_e32 v2, 4, v10
	v_or_b32_e32 v183, v9, v2
	v_or_b32_e32 v182, v8, v2
	v_lshl_add_u64 v[180:181], s[58:59], 0, v[0:1]
	s_mov_b64 s[30:31], 0
	v_mov_b32_e32 v141, v140
	v_mov_b32_e32 v142, v140
	v_mov_b32_e32 v143, v140
	v_mov_b32_e32 v0, v140
	v_mov_b32_e32 v1, v140
	v_mov_b32_e32 v2, v140
	v_mov_b32_e32 v3, v140
	v_mov_b32_e32 v4, v140
	v_mov_b32_e32 v5, v140
	v_mov_b32_e32 v6, v140
	v_mov_b32_e32 v7, v140
	v_mov_b32_e32 v8, v140
	v_mov_b32_e32 v9, v140
	v_mov_b32_e32 v10, v140
	v_mov_b32_e32 v11, v140
	v_mov_b32_e32 v12, v140
	v_mov_b32_e32 v13, v140
	v_mov_b32_e32 v14, v140
	v_mov_b32_e32 v15, v140
	v_mov_b32_e32 v16, v140
	v_mov_b32_e32 v17, v140
	v_mov_b32_e32 v18, v140
	v_mov_b32_e32 v19, v140
	v_mov_b32_e32 v28, v140
	v_mov_b32_e32 v29, v140
	v_mov_b32_e32 v30, v140
	v_mov_b32_e32 v31, v140
	v_mov_b32_e32 v32, v140
	v_mov_b32_e32 v33, v140
	v_mov_b32_e32 v34, v140
	v_mov_b32_e32 v35, v140
	v_mov_b32_e32 v36, v140
	v_mov_b32_e32 v37, v140
	v_mov_b32_e32 v38, v140
	v_mov_b32_e32 v39, v140
	v_mov_b32_e32 v44, v140
	v_mov_b32_e32 v45, v140
	v_mov_b32_e32 v46, v140
	v_mov_b32_e32 v47, v140
	v_mov_b32_e32 v52, v140
	v_mov_b32_e32 v53, v140
	v_mov_b32_e32 v54, v140
	v_mov_b32_e32 v55, v140
	v_mov_b32_e32 v60, v140
	v_mov_b32_e32 v61, v140
	v_mov_b32_e32 v62, v140
	v_mov_b32_e32 v63, v140
	v_mov_b32_e32 v64, v140
	v_mov_b32_e32 v65, v140
	v_mov_b32_e32 v66, v140
	v_mov_b32_e32 v67, v140
	v_mov_b32_e32 v76, v140
	v_mov_b32_e32 v77, v140
	v_mov_b32_e32 v78, v140
	v_mov_b32_e32 v79, v140
	v_mov_b32_e32 v80, v140
	v_mov_b32_e32 v81, v140
	v_mov_b32_e32 v82, v140
	v_mov_b32_e32 v83, v140
	v_mov_b32_e32 v88, v140
	v_mov_b32_e32 v89, v140
	v_mov_b32_e32 v90, v140
	v_mov_b32_e32 v91, v140
	v_mov_b32_e32 v96, v140
	v_mov_b32_e32 v97, v140
	v_mov_b32_e32 v98, v140
	v_mov_b32_e32 v99, v140
	v_mov_b32_e32 v100, v140
	v_mov_b32_e32 v101, v140
	v_mov_b32_e32 v102, v140
	v_mov_b32_e32 v103, v140
	v_mov_b32_e32 v108, v140
	v_mov_b32_e32 v109, v140
	v_mov_b32_e32 v110, v140
	v_mov_b32_e32 v111, v140
	v_mov_b32_e32 v120, v140
	v_mov_b32_e32 v121, v140
	v_mov_b32_e32 v122, v140
	v_mov_b32_e32 v123, v140
	v_mov_b32_e32 v124, v140
	v_mov_b32_e32 v125, v140
	v_mov_b32_e32 v126, v140
	v_mov_b32_e32 v127, v140
	v_mov_b32_e32 v128, v140
	v_mov_b32_e32 v129, v140
	v_mov_b32_e32 v130, v140
	v_mov_b32_e32 v131, v140
	v_mov_b32_e32 v132, v140
	v_mov_b32_e32 v133, v140
	v_mov_b32_e32 v134, v140
	v_mov_b32_e32 v135, v140
	v_mov_b32_e32 v136, v140
	v_mov_b32_e32 v137, v140
	v_mov_b32_e32 v138, v140
	v_mov_b32_e32 v139, v140
	v_mov_b32_e32 v144, v140
	v_mov_b32_e32 v145, v140
	v_mov_b32_e32 v146, v140
	v_mov_b32_e32 v147, v140
	v_mov_b32_e32 v148, v140
	v_mov_b32_e32 v149, v140
	v_mov_b32_e32 v150, v140
	v_mov_b32_e32 v151, v140
	v_mov_b32_e32 v152, v140
	v_mov_b32_e32 v153, v140
	v_mov_b32_e32 v154, v140
	v_mov_b32_e32 v155, v140
	v_mov_b32_e32 v156, v140
	v_mov_b32_e32 v157, v140
	v_mov_b32_e32 v158, v140
	v_mov_b32_e32 v159, v140
	v_mov_b32_e32 v160, v140
	v_mov_b32_e32 v161, v140
	v_mov_b32_e32 v162, v140
	v_mov_b32_e32 v163, v140
	v_mov_b32_e32 v164, v140
	v_mov_b32_e32 v165, v140
	v_mov_b32_e32 v166, v140
	v_mov_b32_e32 v167, v140
	v_mov_b32_e32 v168, v140
	v_mov_b32_e32 v169, v140
	v_mov_b32_e32 v170, v140
	v_mov_b32_e32 v171, v140
	v_mov_b32_e32 v172, v140
	v_mov_b32_e32 v173, v140
	v_mov_b32_e32 v174, v140
	v_mov_b32_e32 v175, v140
	s_mov_b32 s15, 0xad00000
	s_mov_b32 s17, 0xad04000
	s_mov_b32 s52, 0xad08000
	s_mov_b32 s53, 0xad0c000
	s_mov_b32 s10, 0xad10000
	s_mov_b32 s11, 0xad14000
	s_mov_b32 s12, 0xad18000
	s_mov_b32 s13, 0xad1c000
	s_setprio 2
	v_readlane_b32 s98, v253, 3
	v_readlane_b32 s99, v253, 4
	v_and_b32_e32 v224, 15, v188
	v_bfe_u32 v225, v188, 4, 2
	v_lshrrev_b32_e32 v226, 2, v224
	v_sub_u32_e32 v226, 0, v226
	v_and_b32_e32 v226, 3, v226
	v_xor_b32_e32 v225, v225, v226
	v_lshlrev_b32_e32 v225, 4, v225
	v_lshl_or_b32 v225, v224, 6, v225
	v_bfe_u32 v226, v188, 7, 1
	v_lshl_or_b32 v185, v226, 13, v225
	v_bfe_u32 v226, v188, 6, 1
	v_lshl_or_b32 v184, v226, 12, v225
	v_add_u32_e32 v184, 0x4000, v184
	v_lshrrev_b32_e32 v224, 3, v188
	v_bfe_u32 v225, v188, 2, 1
	v_lshrrev_b32_e32 v226, 2, v224
	v_sub_u32_e32 v226, 0, v226
	v_and_b32_e32 v226, 3, v226
	v_and_b32_e32 v227, 3, v188
	v_xor_b32_e32 v226, v227, v226
	v_lshlrev_b32_e32 v226, 4, v226
	v_xor_b32_e32 v224, v224, v225
	v_lshl_or_b32 v226, v224, 6, v226
	v_mul_u32_u24_e32 v225, 0x6000, v225
	v_add_u32_e32 v183, v225, v226
	s_mov_b32 m0, 0
	s_sub_u32 vcc_lo, s30, s98
	v_add_u32_e32 v186, vcc_lo, v178
	v_add_u32_e32 v187, vcc_lo, v180
	v_add_u32_e32 v190, s15, v187
	global_load_dwordx4 v[190:193], v190, s[98:99] offset:128
	v_add_u32_e32 v194, s17, v187
	global_load_dwordx4 v[194:197], v194, s[98:99] offset:128
	v_add_u32_e32 v198, s52, v187
	global_load_dwordx4 v[198:201], v198, s[98:99] offset:128
	v_add_u32_e32 v204, s53, v187
	global_load_dwordx4 v[204:207], v204, s[98:99] offset:128
	v_add_u32_e32 v208, s10, v187
	global_load_dwordx4 v[208:211], v208, s[98:99] offset:128
	v_add_u32_e32 v212, s11, v187
	global_load_dwordx4 v[212:215], v212, s[98:99] offset:128
	v_add_u32_e32 v216, s12, v187
	global_load_dwordx4 v[216:219], v216, s[98:99] offset:128
	v_add_u32_e32 v220, s13, v187
	global_load_dwordx4 v[220:223], v220, s[98:99] offset:128
	v_mov_b32_e32 v224, v186
	global_load_dwordx4 v[224:227], v224, s[98:99] offset:128
	v_add_u32_e32 v228, s16, v186
	global_load_dwordx4 v[228:231], v228, s[98:99] offset:128
	v_add_u32_e32 v232, s95, v186
	global_load_dwordx4 v[232:235], v232, s[98:99] offset:128
	v_add_u32_e32 v236, s28, v186
	global_load_dwordx4 v[236:239], v236, s[98:99] offset:128
	s_barrier
	s_waitcnt vmcnt(12)
	ds_write_b128 v183, v[116:119]
	ds_write_b128 v183, v[112:115] offset:2048
	ds_write_b128 v183, v[104:107] offset:4096
	ds_write_b128 v183, v[92:95] offset:6144
	ds_write_b128 v183, v[84:87] offset:8192
	ds_write_b128 v183, v[72:75] offset:10240
	ds_write_b128 v183, v[68:71] offset:12288
	ds_write_b128 v183, v[48:51] offset:14336
	ds_write_b128 v183, v[56:59] offset:16384
	ds_write_b128 v183, v[40:43] offset:18432
	ds_write_b128 v183, v[24:27] offset:20480
	ds_write_b128 v183, v[20:23] offset:22528
	v_cmp_gt_u32_e32 vcc, 0x6000, v183
	v_add_u32_e32 v182, 0xc000, v183
	v_add_u32_e32 v183, 0xffffa000, v183
	s_nop 0
	v_cndmask_b32_e32 v183, v183, v182, vcc
	s_waitcnt vmcnt(0)
	v_mov_b64_e32 v[116:117], v[190:191]
	v_mov_b64_e32 v[118:119], v[192:193]
	v_mov_b64_e32 v[112:113], v[194:195]
	v_mov_b64_e32 v[114:115], v[196:197]
	v_mov_b64_e32 v[104:105], v[198:199]
	v_mov_b64_e32 v[106:107], v[200:201]
	v_mov_b64_e32 v[92:93], v[204:205]
	v_mov_b64_e32 v[94:95], v[206:207]
	v_mov_b64_e32 v[84:85], v[208:209]
	v_mov_b64_e32 v[86:87], v[210:211]
	v_mov_b64_e32 v[72:73], v[212:213]
	v_mov_b64_e32 v[74:75], v[214:215]
	v_mov_b64_e32 v[68:69], v[216:217]
	v_mov_b64_e32 v[70:71], v[218:219]
	v_mov_b64_e32 v[48:49], v[220:221]
	v_mov_b64_e32 v[50:51], v[222:223]
	v_mov_b64_e32 v[56:57], v[224:225]
	v_mov_b64_e32 v[58:59], v[226:227]
	v_mov_b64_e32 v[40:41], v[228:229]
	v_mov_b64_e32 v[42:43], v[230:231]
	v_mov_b64_e32 v[24:25], v[232:233]
	v_mov_b64_e32 v[26:27], v[234:235]
	v_mov_b64_e32 v[20:21], v[236:237]
	v_mov_b64_e32 v[22:23], v[238:239]
	s_add_u32 s30, s30, 0x80
	s_addc_u32 s31, s31, 0

.LBB0_426:
	s_and_b64 vcc, exec, s[30:31]
	s_cbranch_vccz .LBB0_430
	s_nop 5
	v_mov_b32_e32 v6, v188
	s_mov_b32 s15, 0x1c000
	v_ashrrev_i32_e32 v7, 3, v6
	v_lshlrev_b32_e32 v4, 4, v6
	v_and_b32_e32 v176, 0x70, v4
	v_add_u32_e32 v4, s94, v7
	v_ashrrev_i32_e32 v5, 31, v4
	v_add_u32_e32 v0, s8, v7
	v_lshlrev_b64 v[4:5], 9, v[4:5]
	v_ashrrev_i32_e32 v1, 31, v0
	v_lshl_add_u64 v[4:5], s[42:43], 0, v[4:5]
	v_xor_b32_e32 v8, v7, v6
	v_lshlrev_b64 v[0:1], 9, v[0:1]
	v_lshl_add_u64 v[178:179], v[4:5], 0, v[176:177]
	v_lshlrev_b32_e32 v4, 4, v8
	v_lshl_add_u64 v[2:3], s[46:47], 0, v[0:1]
	v_and_b32_e32 v4, 0x70, v4
	v_lshl_add_u64 v[2:3], v[2:3], 0, v[176:177]
	v_lshl_or_b32 v176, v7, 7, v4
	v_lshrrev_b32_e32 v4, 4, v6
	v_and_b32_e32 v11, 7, v6
	v_bitop3_b32 v12, v4, v11, 3 bitop3:0x6c
	v_add_co_u32_e32 v4, vcc, s28, v178
	s_mov_b32 s42, 0x8000
	s_nop 0
	v_addc_co_u32_e32 v5, vcc, 0, v179, vcc
	v_lshlrev_b32_e32 v8, 7, v6
	v_bfe_u32 v10, v6, 4, 2
	v_add_co_u32_e32 v6, vcc, s42, v178
	s_movk_i32 s43, 0x4000
	s_nop 0
	v_addc_co_u32_e32 v7, vcc, 0, v179, vcc
	global_load_dwordx4 v[20:23], v[4:5], off
	global_load_dwordx4 v[24:27], v[6:7], off
	v_add_co_u32_e32 v4, vcc, s43, v178
	v_and_b32_e32 v9, 0xffffc780, v8
	s_nop 0
	v_addc_co_u32_e32 v5, vcc, 0, v179, vcc
	v_add_co_u32_e32 v6, vcc, s15, v2
	s_mov_b32 s15, 0x18000
	s_nop 0
	v_addc_co_u32_e32 v7, vcc, 0, v3, vcc
	global_load_dwordx4 v[40:43], v[4:5], off
	global_load_dwordx4 v[48:51], v[6:7], off
	v_add_co_u32_e32 v4, vcc, s15, v2
	s_mov_b32 s15, 0x14000
	s_nop 0
	v_addc_co_u32_e32 v5, vcc, 0, v3, vcc
	v_add_co_u32_e32 v6, vcc, s15, v2
	v_and_b32_e32 v8, 0x2780, v8
	s_nop 0
	v_addc_co_u32_e32 v7, vcc, 0, v3, vcc
	global_load_dwordx4 v[68:71], v[4:5], off
	global_load_dwordx4 v[72:75], v[6:7], off
	v_add_co_u32_e32 v4, vcc, s14, v2
	v_bitop3_b32 v10, v10, v11, 4 bitop3:0x36
	s_nop 0
	v_addc_co_u32_e32 v5, vcc, 0, v3, vcc
	v_add_co_u32_e32 v6, vcc, s28, v2
	v_lshl_or_b32 v0, v11, 4, v0
	s_nop 0
	v_addc_co_u32_e32 v7, vcc, 0, v3, vcc
	global_load_dwordx4 v[84:87], v[4:5], off
	global_load_dwordx4 v[92:95], v[6:7], off
	v_add_co_u32_e32 v4, vcc, s42, v2
	v_mov_b32_e32 v140, 0
	s_nop 0
	v_addc_co_u32_e32 v5, vcc, 0, v3, vcc
	v_add_co_u32_e32 v6, vcc, s43, v2
	v_lshl_add_u64 v[180:181], s[58:59], 0, v[0:1]
	s_nop 0
	v_addc_co_u32_e32 v7, vcc, 0, v3, vcc
	global_load_dwordx4 v[104:107], v[4:5], off
	global_load_dwordx4 v[112:115], v[6:7], off
	global_load_dwordx4 v[56:59], v[178:179], off
	global_load_dwordx4 v[116:119], v[2:3], off
	v_lshlrev_b32_e32 v2, 4, v12
	v_or_b32_e32 v185, v9, v2
	v_or_b32_e32 v184, v8, v2
	v_lshlrev_b32_e32 v2, 4, v10
	v_or_b32_e32 v183, v9, v2
	v_or_b32_e32 v182, v8, v2
	s_mov_b64 s[30:31], 0
	v_mov_b32_e32 v141, v140
	v_mov_b32_e32 v142, v140
	v_mov_b32_e32 v143, v140
	v_mov_b32_e32 v0, v140
	v_mov_b32_e32 v1, v140
	v_mov_b32_e32 v2, v140
	v_mov_b32_e32 v3, v140
	v_mov_b32_e32 v4, v140
	v_mov_b32_e32 v5, v140
	v_mov_b32_e32 v6, v140
	v_mov_b32_e32 v7, v140
	v_mov_b32_e32 v8, v140
	v_mov_b32_e32 v9, v140
	v_mov_b32_e32 v10, v140
	v_mov_b32_e32 v11, v140
	v_mov_b32_e32 v12, v140
	v_mov_b32_e32 v13, v140
	v_mov_b32_e32 v14, v140
	v_mov_b32_e32 v15, v140
	v_mov_b32_e32 v16, v140
	v_mov_b32_e32 v17, v140
	v_mov_b32_e32 v18, v140
	v_mov_b32_e32 v19, v140
	v_mov_b32_e32 v28, v140
	v_mov_b32_e32 v29, v140
	v_mov_b32_e32 v30, v140
	v_mov_b32_e32 v31, v140
	v_mov_b32_e32 v32, v140
	v_mov_b32_e32 v33, v140
	v_mov_b32_e32 v34, v140
	v_mov_b32_e32 v35, v140
	v_mov_b32_e32 v36, v140
	v_mov_b32_e32 v37, v140
	v_mov_b32_e32 v38, v140
	v_mov_b32_e32 v39, v140
	v_mov_b32_e32 v44, v140
	v_mov_b32_e32 v45, v140
	v_mov_b32_e32 v46, v140
	v_mov_b32_e32 v47, v140
	v_mov_b32_e32 v52, v140
	v_mov_b32_e32 v53, v140
	v_mov_b32_e32 v54, v140
	v_mov_b32_e32 v55, v140
	v_mov_b32_e32 v60, v140
	v_mov_b32_e32 v61, v140
	v_mov_b32_e32 v62, v140
	v_mov_b32_e32 v63, v140
	v_mov_b32_e32 v64, v140
	v_mov_b32_e32 v65, v140
	v_mov_b32_e32 v66, v140
	v_mov_b32_e32 v67, v140
	v_mov_b32_e32 v76, v140
	v_mov_b32_e32 v77, v140
	v_mov_b32_e32 v78, v140
	v_mov_b32_e32 v79, v140
	v_mov_b32_e32 v80, v140
	v_mov_b32_e32 v81, v140
	v_mov_b32_e32 v82, v140
	v_mov_b32_e32 v83, v140
	v_mov_b32_e32 v88, v140
	v_mov_b32_e32 v89, v140
	v_mov_b32_e32 v90, v140
	v_mov_b32_e32 v91, v140
	v_mov_b32_e32 v96, v140
	v_mov_b32_e32 v97, v140
	v_mov_b32_e32 v98, v140
	v_mov_b32_e32 v99, v140
	v_mov_b32_e32 v100, v140
	v_mov_b32_e32 v101, v140
	v_mov_b32_e32 v102, v140
	v_mov_b32_e32 v103, v140
	v_mov_b32_e32 v108, v140
	v_mov_b32_e32 v109, v140
	v_mov_b32_e32 v110, v140
	v_mov_b32_e32 v111, v140
	v_mov_b32_e32 v120, v140
	v_mov_b32_e32 v121, v140
	v_mov_b32_e32 v122, v140
	v_mov_b32_e32 v123, v140
	v_mov_b32_e32 v124, v140
	v_mov_b32_e32 v125, v140
	v_mov_b32_e32 v126, v140
	v_mov_b32_e32 v127, v140
	v_mov_b32_e32 v128, v140
	v_mov_b32_e32 v129, v140
	v_mov_b32_e32 v130, v140
	v_mov_b32_e32 v131, v140
	v_mov_b32_e32 v132, v140
	v_mov_b32_e32 v133, v140
	v_mov_b32_e32 v134, v140
	v_mov_b32_e32 v135, v140
	v_mov_b32_e32 v136, v140
	v_mov_b32_e32 v137, v140
	v_mov_b32_e32 v138, v140
	v_mov_b32_e32 v139, v140
	v_mov_b32_e32 v144, v140
	v_mov_b32_e32 v145, v140
	v_mov_b32_e32 v146, v140
	v_mov_b32_e32 v147, v140
	v_mov_b32_e32 v148, v140
	v_mov_b32_e32 v149, v140
	v_mov_b32_e32 v150, v140
	v_mov_b32_e32 v151, v140
	v_mov_b32_e32 v152, v140
	v_mov_b32_e32 v153, v140
	v_mov_b32_e32 v154, v140
	v_mov_b32_e32 v155, v140
	v_mov_b32_e32 v156, v140
	v_mov_b32_e32 v157, v140
	v_mov_b32_e32 v158, v140
	v_mov_b32_e32 v159, v140
	v_mov_b32_e32 v160, v140
	v_mov_b32_e32 v161, v140
	v_mov_b32_e32 v162, v140
	v_mov_b32_e32 v163, v140
	v_mov_b32_e32 v164, v140
	v_mov_b32_e32 v165, v140
	v_mov_b32_e32 v166, v140
	v_mov_b32_e32 v167, v140
	v_mov_b32_e32 v168, v140
	v_mov_b32_e32 v169, v140
	v_mov_b32_e32 v170, v140
	v_mov_b32_e32 v171, v140
	v_mov_b32_e32 v172, v140
	v_mov_b32_e32 v173, v140
	v_mov_b32_e32 v174, v140
	v_mov_b32_e32 v175, v140
	s_mov_b32 s14, 0xad00000
	s_mov_b32 s15, 0xad04000
	s_mov_b32 s16, 0xad08000
	s_mov_b32 s17, 0xad0c000
	s_mov_b32 s10, 0xad10000
	s_mov_b32 s11, 0xad14000
	s_mov_b32 s12, 0xad18000
	s_mov_b32 s13, 0xad1c000
	s_setprio 2
	v_readlane_b32 s98, v253, 3
	v_readlane_b32 s99, v253, 4
	v_and_b32_e32 v224, 15, v188
	v_bfe_u32 v225, v188, 4, 2
	v_lshrrev_b32_e32 v226, 2, v224
	v_sub_u32_e32 v226, 0, v226
	v_and_b32_e32 v226, 3, v226
	v_xor_b32_e32 v225, v225, v226
	v_lshlrev_b32_e32 v225, 4, v225
	v_lshl_or_b32 v225, v224, 6, v225
	v_bfe_u32 v226, v188, 7, 1
	v_lshl_or_b32 v185, v226, 13, v225
	v_bfe_u32 v226, v188, 6, 1
	v_lshl_or_b32 v184, v226, 12, v225
	v_add_u32_e32 v184, 0x4000, v184
	v_lshrrev_b32_e32 v224, 3, v188
	v_bfe_u32 v225, v188, 2, 1
	v_lshrrev_b32_e32 v226, 2, v224
	v_sub_u32_e32 v226, 0, v226
	v_and_b32_e32 v226, 3, v226
	v_and_b32_e32 v227, 3, v188
	v_xor_b32_e32 v226, v227, v226
	v_lshlrev_b32_e32 v226, 4, v226
	v_xor_b32_e32 v224, v224, v225
	v_lshl_or_b32 v226, v224, 6, v226
	v_mul_u32_u24_e32 v225, 0x6000, v225
	v_add_u32_e32 v183, v225, v226
	s_mov_b32 m0, 0
	s_sub_u32 vcc_lo, s30, s98
	v_add_u32_e32 v186, vcc_lo, v178
	v_add_u32_e32 v187, vcc_lo, v180
	v_add_u32_e32 v190, s14, v187
	global_load_dwordx4 v[190:193], v190, s[98:99] offset:128
	v_add_u32_e32 v194, s15, v187
	global_load_dwordx4 v[194:197], v194, s[98:99] offset:128
	v_add_u32_e32 v198, s16, v187
	global_load_dwordx4 v[198:201], v198, s[98:99] offset:128
	v_add_u32_e32 v204, s17, v187
	global_load_dwordx4 v[204:207], v204, s[98:99] offset:128
	v_add_u32_e32 v208, s10, v187
	global_load_dwordx4 v[208:211], v208, s[98:99] offset:128
	v_add_u32_e32 v212, s11, v187
	global_load_dwordx4 v[212:215], v212, s[98:99] offset:128
	v_add_u32_e32 v216, s12, v187
	global_load_dwordx4 v[216:219], v216, s[98:99] offset:128
	v_add_u32_e32 v220, s13, v187
	global_load_dwordx4 v[220:223], v220, s[98:99] offset:128
	v_mov_b32_e32 v224, v186
	global_load_dwordx4 v[224:227], v224, s[98:99] offset:128
	v_add_u32_e32 v228, s43, v186
	global_load_dwordx4 v[228:231], v228, s[98:99] offset:128
	v_add_u32_e32 v232, s42, v186
	global_load_dwordx4 v[232:235], v232, s[98:99] offset:128
	v_add_u32_e32 v236, s28, v186
	global_load_dwordx4 v[236:239], v236, s[98:99] offset:128
	s_barrier
	s_waitcnt vmcnt(12)
	ds_write_b128 v183, v[116:119]
	ds_write_b128 v183, v[112:115] offset:2048
	ds_write_b128 v183, v[104:107] offset:4096
	ds_write_b128 v183, v[92:95] offset:6144
	ds_write_b128 v183, v[84:87] offset:8192
	ds_write_b128 v183, v[72:75] offset:10240
	ds_write_b128 v183, v[68:71] offset:12288
	ds_write_b128 v183, v[48:51] offset:14336
	ds_write_b128 v183, v[56:59] offset:16384
	ds_write_b128 v183, v[40:43] offset:18432
	ds_write_b128 v183, v[24:27] offset:20480
	ds_write_b128 v183, v[20:23] offset:22528
	v_cmp_gt_u32_e32 vcc, 0x6000, v183
	v_add_u32_e32 v182, 0xc000, v183
	v_add_u32_e32 v183, 0xffffa000, v183
	s_nop 0
	v_cndmask_b32_e32 v183, v183, v182, vcc
	s_waitcnt vmcnt(0)
	v_mov_b64_e32 v[116:117], v[190:191]
	v_mov_b64_e32 v[118:119], v[192:193]
	v_mov_b64_e32 v[112:113], v[194:195]
	v_mov_b64_e32 v[114:115], v[196:197]
	v_mov_b64_e32 v[104:105], v[198:199]
	v_mov_b64_e32 v[106:107], v[200:201]
	v_mov_b64_e32 v[92:93], v[204:205]
	v_mov_b64_e32 v[94:95], v[206:207]
	v_mov_b64_e32 v[84:85], v[208:209]
	v_mov_b64_e32 v[86:87], v[210:211]
	v_mov_b64_e32 v[72:73], v[212:213]
	v_mov_b64_e32 v[74:75], v[214:215]
	v_mov_b64_e32 v[68:69], v[216:217]
	v_mov_b64_e32 v[70:71], v[218:219]
	v_mov_b64_e32 v[48:49], v[220:221]
	v_mov_b64_e32 v[50:51], v[222:223]
	v_mov_b64_e32 v[56:57], v[224:225]
	v_mov_b64_e32 v[58:59], v[226:227]
	v_mov_b64_e32 v[40:41], v[228:229]
	v_mov_b64_e32 v[42:43], v[230:231]
	v_mov_b64_e32 v[24:25], v[232:233]
	v_mov_b64_e32 v[26:27], v[234:235]
	v_mov_b64_e32 v[20:21], v[236:237]
	v_mov_b64_e32 v[22:23], v[238:239]
	s_add_u32 s30, s30, 0x80
	s_addc_u32 s31, s31, 0

.LBB0_486:
	s_ashr_i32 s30, s36, 3
	s_lshl_b32 s40, s30, 1
	s_and_b32 s31, s30, -16
	s_and_b32 s40, s40, 14
	s_or_b32 s31, s40, s31
	s_bfe_u32 s40, s30, 0x10003
	s_or_b32 s31, s31, s40
	s_cmp_lt_i32 s30, 0
	s_cselect_b32 s30, s31, s30
	s_and_b32 s31, s36, 7
	s_mul_i32 s31, s31, 56
	s_add_i32 s30, s30, s31
	s_mul_hi_i32 s31, s30, 0x92492493
	s_add_i32 s31, s31, s30
	s_ashr_i32 s40, s31, 4
	s_lshr_b32 s41, s31, 31
	s_add_i32 s40, s40, s41
	s_mul_i32 s42, s40, 0xffffffe4
	s_add_i32 s42, s42, s30
	s_ashr_i32 s30, s31, 5
	s_mul_hi_i32 s31, s42, 0x92492493
	s_add_i32 s31, s31, s42
	s_add_i32 s30, s30, s41
	s_lshr_b32 s41, s31, 31
	s_ashr_i32 s31, s31, 2
	s_add_i32 s31, s31, s41
	s_lshl_b32 s41, s30, 1
	s_add_i32 s41, s41, s31
	s_sub_i32 s40, s40, s41
	s_mul_i32 s40, s40, 7
	s_add_i32 s41, s40, s42
	v_mov_b32_e32 v8, v188
	s_lshl_b32 s30, s30, 10
	s_lshl_b32 s40, s31, 8
	s_lshl_b32 s41, s41, 7
	s_add_i32 s40, s40, s30
	v_ashrrev_i32_e32 v9, 3, v8
	v_lshlrev_b32_e32 v4, 4, v8
	v_and_b32_e32 v176, 0x70, v4
	v_add_u32_e32 v4, s41, v9
	v_add_u32_e32 v0, s40, v9
	v_ashrrev_i32_e32 v5, 31, v4
	v_ashrrev_i32_e32 v1, 31, v0
	v_lshlrev_b64 v[4:5], 11, v[4:5]
	v_xor_b32_e32 v10, v9, v8
	v_lshlrev_b64 v[0:1], 11, v[0:1]
	v_lshl_add_u64 v[6:7], s[22:23], 0, v[4:5]
	v_lshlrev_b32_e32 v10, 4, v10
	v_lshl_add_u64 v[2:3], s[0:1], 0, v[0:1]
	v_lshl_add_u64 v[6:7], v[6:7], 0, v[176:177]
	v_and_b32_e32 v10, 0x70, v10
	s_mov_b32 s30, 0x30000
	v_lshl_add_u64 v[2:3], v[2:3], 0, v[176:177]
	v_lshl_or_b32 v176, v9, 7, v10
	v_lshlrev_b32_e32 v12, 7, v8
	v_lshrrev_b32_e32 v9, 4, v8
	v_bfe_u32 v14, v8, 4, 2
	v_and_b32_e32 v15, 7, v8
	v_add_co_u32_e32 v8, vcc, s30, v6
	v_bitop3_b32 v16, v9, v15, 3 bitop3:0x6c
	s_nop 0
	v_addc_co_u32_e32 v9, vcc, 0, v7, vcc
	s_mov_b32 s31, 0x20000
	v_add_co_u32_e32 v10, vcc, s31, v6
	s_mov_b32 s42, 0x10000
	s_nop 0
	v_addc_co_u32_e32 v11, vcc, 0, v7, vcc
	global_load_dwordx4 v[56:59], v[8:9], off
	global_load_dwordx4 v[64:67], v[10:11], off
	v_add_co_u32_e32 v8, vcc, s42, v6
	s_mov_b32 s43, 0x70000
	s_nop 0
	v_addc_co_u32_e32 v9, vcc, 0, v7, vcc
	v_add_co_u32_e32 v10, vcc, s43, v2
	s_mov_b32 s43, 0x60000
	s_nop 0
	v_addc_co_u32_e32 v11, vcc, 0, v3, vcc
	global_load_dwordx4 v[76:79], v[8:9], off
	global_load_dwordx4 v[84:87], v[10:11], off
	v_add_co_u32_e32 v8, vcc, s43, v2
	s_mov_b32 s43, 0x50000
	s_nop 0
	v_addc_co_u32_e32 v9, vcc, 0, v3, vcc
	v_add_co_u32_e32 v10, vcc, s43, v2
	s_mov_b32 s43, 0x40000
	s_nop 0
	v_addc_co_u32_e32 v11, vcc, 0, v3, vcc
	global_load_dwordx4 v[100:103], v[8:9], off
	global_load_dwordx4 v[104:107], v[10:11], off
	v_add_co_u32_e32 v8, vcc, s43, v2
	v_and_b32_e32 v13, 0xffffc780, v12
	s_nop 0
	v_addc_co_u32_e32 v9, vcc, 0, v3, vcc
	v_add_co_u32_e32 v10, vcc, s30, v2
	v_and_b32_e32 v12, 0x2780, v12
	s_nop 0
	v_addc_co_u32_e32 v11, vcc, 0, v3, vcc
	global_load_dwordx4 v[124:127], v[8:9], off
	global_load_dwordx4 v[128:131], v[10:11], off
	v_add_co_u32_e32 v8, vcc, s31, v2
	v_bitop3_b32 v14, v14, v15, 4 bitop3:0x36
	s_nop 0
	v_addc_co_u32_e32 v9, vcc, 0, v3, vcc
	v_add_co_u32_e32 v10, vcc, s42, v2
	v_mov_b32_e32 v116, 0
	s_nop 0
	v_addc_co_u32_e32 v11, vcc, 0, v3, vcc
	global_load_dwordx4 v[148:151], v[8:9], off
	global_load_dwordx4 v[152:155], v[10:11], off
	global_load_dwordx4 v[140:143], v[6:7], off
	global_load_dwordx4 v[160:163], v[2:3], off
	v_lshlrev_b32_e32 v2, 4, v16
	v_or_b32_e32 v185, v13, v2
	v_or_b32_e32 v184, v12, v2
	v_lshlrev_b32_e32 v2, 4, v14
	v_or_b32_e32 v183, v13, v2
	v_or_b32_e32 v182, v12, v2
	v_lshlrev_b32_e32 v2, 4, v15
	v_or_b32_e32 v0, v0, v2
	v_or_b32_e32 v4, v4, v2
	v_lshl_add_u64 v[178:179], s[34:35], 0, v[0:1]
	v_lshl_add_u64 v[180:181], s[2:3], 0, v[4:5]
	s_mov_b64 s[30:31], 0
	v_mov_b32_e32 v117, v116
	v_mov_b32_e32 v118, v116
	v_mov_b32_e32 v119, v116
	v_mov_b32_e32 v0, v116
	v_mov_b32_e32 v1, v116
	v_mov_b32_e32 v2, v116
	v_mov_b32_e32 v3, v116
	v_mov_b32_e32 v4, v116
	v_mov_b32_e32 v5, v116
	v_mov_b32_e32 v6, v116
	v_mov_b32_e32 v7, v116
	v_mov_b32_e32 v8, v116
	v_mov_b32_e32 v9, v116
	v_mov_b32_e32 v10, v116
	v_mov_b32_e32 v11, v116
	v_mov_b32_e32 v12, v116
	v_mov_b32_e32 v13, v116
	v_mov_b32_e32 v14, v116
	v_mov_b32_e32 v15, v116
	v_mov_b32_e32 v16, v116
	v_mov_b32_e32 v17, v116
	v_mov_b32_e32 v18, v116
	v_mov_b32_e32 v19, v116
	v_mov_b32_e32 v20, v116
	v_mov_b32_e32 v21, v116
	v_mov_b32_e32 v22, v116
	v_mov_b32_e32 v23, v116
	v_mov_b32_e32 v24, v116
	v_mov_b32_e32 v25, v116
	v_mov_b32_e32 v26, v116
	v_mov_b32_e32 v27, v116
	v_mov_b32_e32 v28, v116
	v_mov_b32_e32 v29, v116
	v_mov_b32_e32 v30, v116
	v_mov_b32_e32 v31, v116
	v_mov_b32_e32 v32, v116
	v_mov_b32_e32 v33, v116
	v_mov_b32_e32 v34, v116
	v_mov_b32_e32 v35, v116
	v_mov_b32_e32 v36, v116
	v_mov_b32_e32 v37, v116
	v_mov_b32_e32 v38, v116
	v_mov_b32_e32 v39, v116
	v_mov_b32_e32 v40, v116
	v_mov_b32_e32 v41, v116
	v_mov_b32_e32 v42, v116
	v_mov_b32_e32 v43, v116
	v_mov_b32_e32 v44, v116
	v_mov_b32_e32 v45, v116
	v_mov_b32_e32 v46, v116
	v_mov_b32_e32 v47, v116
	v_mov_b32_e32 v48, v116
	v_mov_b32_e32 v49, v116
	v_mov_b32_e32 v50, v116
	v_mov_b32_e32 v51, v116
	v_mov_b32_e32 v52, v116
	v_mov_b32_e32 v53, v116
	v_mov_b32_e32 v54, v116
	v_mov_b32_e32 v55, v116
	v_mov_b32_e32 v60, v116
	v_mov_b32_e32 v61, v116
	v_mov_b32_e32 v62, v116
	v_mov_b32_e32 v63, v116
	v_mov_b32_e32 v68, v116
	v_mov_b32_e32 v69, v116
	v_mov_b32_e32 v70, v116
	v_mov_b32_e32 v71, v116
	v_mov_b32_e32 v72, v116
	v_mov_b32_e32 v73, v116
	v_mov_b32_e32 v74, v116
	v_mov_b32_e32 v75, v116
	v_mov_b32_e32 v80, v116
	v_mov_b32_e32 v81, v116
	v_mov_b32_e32 v82, v116
	v_mov_b32_e32 v83, v116
	v_mov_b32_e32 v88, v116
	v_mov_b32_e32 v89, v116
	v_mov_b32_e32 v90, v116
	v_mov_b32_e32 v91, v116
	v_mov_b32_e32 v92, v116
	v_mov_b32_e32 v93, v116
	v_mov_b32_e32 v94, v116
	v_mov_b32_e32 v95, v116
	v_mov_b32_e32 v96, v116
	v_mov_b32_e32 v97, v116
	v_mov_b32_e32 v98, v116
	v_mov_b32_e32 v99, v116
	v_mov_b32_e32 v108, v116
	v_mov_b32_e32 v109, v116
	v_mov_b32_e32 v110, v116
	v_mov_b32_e32 v111, v116
	v_mov_b32_e32 v112, v116
	v_mov_b32_e32 v113, v116
	v_mov_b32_e32 v114, v116
	v_mov_b32_e32 v115, v116
	v_mov_b32_e32 v120, v116
	v_mov_b32_e32 v121, v116
	v_mov_b32_e32 v122, v116
	v_mov_b32_e32 v123, v116
	v_mov_b32_e32 v132, v116
	v_mov_b32_e32 v133, v116
	v_mov_b32_e32 v134, v116
	v_mov_b32_e32 v135, v116
	v_mov_b32_e32 v136, v116
	v_mov_b32_e32 v137, v116
	v_mov_b32_e32 v138, v116
	v_mov_b32_e32 v139, v116
	v_mov_b32_e32 v144, v116
	v_mov_b32_e32 v145, v116
	v_mov_b32_e32 v146, v116
	v_mov_b32_e32 v147, v116
	v_mov_b32_e32 v156, v116
	v_mov_b32_e32 v157, v116
	v_mov_b32_e32 v158, v116
	v_mov_b32_e32 v159, v116
	v_mov_b32_e32 v164, v116
	v_mov_b32_e32 v165, v116
	v_mov_b32_e32 v166, v116
	v_mov_b32_e32 v167, v116
	v_mov_b32_e32 v168, v116
	v_mov_b32_e32 v169, v116
	v_mov_b32_e32 v170, v116
	v_mov_b32_e32 v171, v116
	v_mov_b32_e32 v172, v116
	v_mov_b32_e32 v173, v116
	v_mov_b32_e32 v174, v116
	v_mov_b32_e32 v175, v116
	s_setprio 2
	v_readlane_b32 s98, v253, 3
	v_readlane_b32 s99, v253, 4
	v_and_b32_e32 v224, 15, v188
	v_bfe_u32 v225, v188, 4, 2
	v_lshrrev_b32_e32 v226, 2, v224
	v_sub_u32_e32 v226, 0, v226
	v_and_b32_e32 v226, 3, v226
	v_xor_b32_e32 v225, v225, v226
	v_lshlrev_b32_e32 v225, 4, v225
	v_lshl_or_b32 v225, v224, 6, v225
	v_bfe_u32 v226, v188, 7, 1
	v_lshl_or_b32 v185, v226, 13, v225
	v_bfe_u32 v226, v188, 6, 1
	v_lshl_or_b32 v184, v226, 12, v225
	v_add_u32_e32 v184, 0x4000, v184
	v_lshrrev_b32_e32 v224, 3, v188
	v_bfe_u32 v225, v188, 2, 1
	v_lshrrev_b32_e32 v226, 2, v224
	v_sub_u32_e32 v226, 0, v226
	v_and_b32_e32 v226, 3, v226
	v_and_b32_e32 v227, 3, v188
	v_xor_b32_e32 v226, v227, v226
	v_lshlrev_b32_e32 v226, 4, v226
	v_xor_b32_e32 v224, v224, v225
	v_lshl_or_b32 v226, v224, 6, v226
	v_mul_u32_u24_e32 v225, 0x6000, v225
	v_add_u32_e32 v183, v225, v226
	s_mov_b32 m0, 0
	s_sub_u32 vcc_lo, s30, s98
	v_add_u32_e32 v186, vcc_lo, v178
	v_add_u32_e32 v187, vcc_lo, v180
	v_add_u32_e32 v190, s26, v186
	global_load_dwordx4 v[190:193], v190, s[98:99] offset:128
	v_add_u32_e32 v194, s27, v186
	global_load_dwordx4 v[194:197], v194, s[98:99] offset:128
	v_add_u32_e32 v198, s20, v186
	global_load_dwordx4 v[198:201], v198, s[98:99] offset:128
	v_add_u32_e32 v204, s21, v186
	global_load_dwordx4 v[204:207], v204, s[98:99] offset:128
	v_add_u32_e32 v208, s56, v186
	global_load_dwordx4 v[208:211], v208, s[98:99] offset:128
	v_add_u32_e32 v212, s57, v186
	global_load_dwordx4 v[212:215], v212, s[98:99] offset:128
	v_add_u32_e32 v216, s24, v186
	global_load_dwordx4 v[216:219], v216, s[98:99] offset:128
	v_add_u32_e32 v220, s96, v186
	global_load_dwordx4 v[220:223], v220, s[98:99] offset:128
	v_add_u32_e32 v224, 0x1800000, v187
	global_load_dwordx4 v[224:227], v224, s[98:99] offset:128
	v_add_u32_e32 v228, 0x1810000, v187
	global_load_dwordx4 v[228:231], v228, s[98:99] offset:128
	v_add_u32_e32 v232, 0x1820000, v187
	global_load_dwordx4 v[232:235], v232, s[98:99] offset:128
	v_add_u32_e32 v236, 0x1830000, v187
	global_load_dwordx4 v[236:239], v236, s[98:99] offset:128
	s_barrier
	s_waitcnt vmcnt(12)
	ds_write_b128 v183, v[160:163]
	ds_write_b128 v183, v[152:155] offset:2048
	ds_write_b128 v183, v[148:151] offset:4096
	ds_write_b128 v183, v[128:131] offset:6144
	ds_write_b128 v183, v[124:127] offset:8192
	ds_write_b128 v183, v[104:107] offset:10240
	ds_write_b128 v183, v[100:103] offset:12288
	ds_write_b128 v183, v[84:87] offset:14336
	ds_write_b128 v183, v[140:143] offset:16384
	ds_write_b128 v183, v[76:79] offset:18432
	ds_write_b128 v183, v[64:67] offset:20480
	ds_write_b128 v183, v[56:59] offset:22528
	v_cmp_gt_u32_e32 vcc, 0x6000, v183
	v_add_u32_e32 v182, 0xc000, v183
	v_add_u32_e32 v183, 0xffffa000, v183
	s_nop 0
	v_cndmask_b32_e32 v183, v183, v182, vcc
	s_waitcnt vmcnt(0)
	v_mov_b64_e32 v[160:161], v[190:191]
	v_mov_b64_e32 v[162:163], v[192:193]
	v_mov_b64_e32 v[152:153], v[194:195]
	v_mov_b64_e32 v[154:155], v[196:197]
	v_mov_b64_e32 v[148:149], v[198:199]
	v_mov_b64_e32 v[150:151], v[200:201]
	v_mov_b64_e32 v[128:129], v[204:205]
	v_mov_b64_e32 v[130:131], v[206:207]
	v_mov_b64_e32 v[124:125], v[208:209]
	v_mov_b64_e32 v[126:127], v[210:211]
	v_mov_b64_e32 v[104:105], v[212:213]
	v_mov_b64_e32 v[106:107], v[214:215]
	v_mov_b64_e32 v[100:101], v[216:217]
	v_mov_b64_e32 v[102:103], v[218:219]
	v_mov_b64_e32 v[84:85], v[220:221]
	v_mov_b64_e32 v[86:87], v[222:223]
	v_mov_b64_e32 v[140:141], v[224:225]
	v_mov_b64_e32 v[142:143], v[226:227]
	v_mov_b64_e32 v[76:77], v[228:229]
	v_mov_b64_e32 v[78:79], v[230:231]
	v_mov_b64_e32 v[64:65], v[232:233]
	v_mov_b64_e32 v[66:67], v[234:235]
	v_mov_b64_e32 v[56:57], v[236:237]
	v_mov_b64_e32 v[58:59], v[238:239]
	s_add_u32 s30, s30, 0x80
	s_addc_u32 s31, s31, 0

.LBB0_801:
	s_waitcnt lgkmcnt(0)
	s_ashr_i32 s6, s8, 3
	s_lshl_b32 s9, s6, 1
	s_and_b32 s7, s6, -16
	s_and_b32 s9, s9, 14
	s_or_b32 s7, s9, s7
	s_bfe_u32 s9, s6, 0x10003
	s_or_b32 s7, s7, s9
	s_cmp_lt_i32 s6, 0
	s_cselect_b32 s6, s7, s6
	s_lshl_b32 s7, s8, 5
	s_and_b32 s7, s7, 0xe0
	s_add_i32 s6, s6, s7
	s_ashr_i32 s7, s6, 31
	s_lshr_b32 s7, s7, 27
	s_add_i32 s7, s6, s7
	s_and_b32 s9, s7, 0xffffffe0
	s_sub_i32 s6, s6, s9
	s_ashr_i32 s9, s6, 31
	s_lshr_b32 s9, s9, 29
	s_add_i32 s9, s6, s9
	s_ashr_i32 s10, s9, 3
	s_lshl_b32 s7, s7, 5
	s_and_b32 s7, s7, 0xfffffc00
	s_lshl_b32 s9, s10, 8
	s_add_i32 s9, s9, s7
	s_lshl_b32 s7, s10, 10
	s_lshl_b32 s6, s6, 7
	v_mov_b32_e32 v6, v188
	s_sub_i32 s10, s6, s7
	s_mov_b32 s11, 0x30000
	v_ashrrev_i32_e32 v7, 3, v6
	v_lshlrev_b32_e32 v4, 4, v6
	v_and_b32_e32 v176, 0x70, v4
	v_add_u32_e32 v4, s10, v7
	v_ashrrev_i32_e32 v5, 31, v4
	v_add_u32_e32 v0, s9, v7
	v_lshlrev_b64 v[4:5], 11, v[4:5]
	v_ashrrev_i32_e32 v1, 31, v0
	v_lshl_add_u64 v[4:5], s[2:3], 0, v[4:5]
	v_xor_b32_e32 v8, v7, v6
	v_lshlrev_b64 v[0:1], 11, v[0:1]
	v_lshl_add_u64 v[178:179], v[4:5], 0, v[176:177]
	v_lshlrev_b32_e32 v4, 4, v8
	v_lshl_add_u64 v[2:3], s[0:1], 0, v[0:1]
	v_and_b32_e32 v4, 0x70, v4
	v_lshl_add_u64 v[2:3], v[2:3], 0, v[176:177]
	v_lshl_or_b32 v176, v7, 7, v4
	v_lshrrev_b32_e32 v4, 4, v6
	v_and_b32_e32 v15, 7, v6
	v_bitop3_b32 v20, v4, v15, 3 bitop3:0x6c
	v_add_co_u32_e32 v4, vcc, s11, v178
	v_lshlrev_b32_e32 v12, 7, v6
	s_nop 0
	v_addc_co_u32_e32 v5, vcc, 0, v179, vcc
	v_bfe_u32 v14, v6, 4, 2
	v_add_co_u32_e32 v6, vcc, s12, v178
	s_mov_b32 s6, 0x70000
	s_nop 0
	v_addc_co_u32_e32 v7, vcc, 0, v179, vcc
	global_load_dwordx4 v[8:11], v[4:5], off
	global_load_dwordx4 v[16:19], v[6:7], off
	v_add_co_u32_e32 v4, vcc, s13, v178
	v_and_b32_e32 v13, 0xffffc780, v12
	s_nop 0
	v_addc_co_u32_e32 v5, vcc, 0, v179, vcc
	v_add_co_u32_e32 v6, vcc, s6, v2
	s_mov_b32 s6, 0x60000
	s_nop 0
	v_addc_co_u32_e32 v7, vcc, 0, v3, vcc
	global_load_dwordx4 v[32:35], v[4:5], off
	global_load_dwordx4 v[40:43], v[6:7], off
	v_add_co_u32_e32 v4, vcc, s6, v2
	s_mov_b32 s6, 0x50000
	s_nop 0
	v_addc_co_u32_e32 v5, vcc, 0, v3, vcc
	v_add_co_u32_e32 v6, vcc, s6, v2
	v_and_b32_e32 v12, 0x2780, v12
	s_nop 0
	v_addc_co_u32_e32 v7, vcc, 0, v3, vcc
	global_load_dwordx4 v[60:63], v[4:5], off
	global_load_dwordx4 v[68:71], v[6:7], off
	v_add_co_u32_e32 v4, vcc, 0x40000, v2
	v_bitop3_b32 v14, v14, v15, 4 bitop3:0x36
	s_nop 0
	v_addc_co_u32_e32 v5, vcc, 0, v3, vcc
	v_add_co_u32_e32 v6, vcc, s11, v2
	v_lshl_or_b32 v0, v15, 4, v0
	s_nop 0
	v_addc_co_u32_e32 v7, vcc, 0, v3, vcc
	global_load_dwordx4 v[80:83], v[4:5], off
	global_load_dwordx4 v[88:91], v[6:7], off
	v_add_co_u32_e32 v4, vcc, s12, v2
	v_mov_b32_e32 v140, 0
	s_nop 0
	v_addc_co_u32_e32 v5, vcc, 0, v3, vcc
	v_add_co_u32_e32 v6, vcc, 0x10000, v2
	v_lshl_add_u64 v[180:181], s[34:35], 0, v[0:1]
	s_nop 0
	v_addc_co_u32_e32 v7, vcc, 0, v3, vcc
	global_load_dwordx4 v[104:107], v[4:5], off
	global_load_dwordx4 v[112:115], v[6:7], off
	global_load_dwordx4 v[56:59], v[178:179], off
	global_load_dwordx4 v[116:119], v[2:3], off
	v_lshlrev_b32_e32 v2, 4, v20
	v_or_b32_e32 v185, v13, v2
	v_or_b32_e32 v184, v12, v2
	v_lshlrev_b32_e32 v2, 4, v14
	v_or_b32_e32 v183, v13, v2
	v_or_b32_e32 v182, v12, v2
	s_mov_b64 s[6:7], 0
	v_mov_b32_e32 v141, v140
	v_mov_b32_e32 v142, v140
	v_mov_b32_e32 v143, v140
	v_mov_b32_e32 v0, v140
	v_mov_b32_e32 v1, v140
	v_mov_b32_e32 v2, v140
	v_mov_b32_e32 v3, v140
	v_mov_b32_e32 v4, v140
	v_mov_b32_e32 v5, v140
	v_mov_b32_e32 v6, v140
	v_mov_b32_e32 v7, v140
	v_mov_b32_e32 v12, v140
	v_mov_b32_e32 v13, v140
	v_mov_b32_e32 v14, v140
	v_mov_b32_e32 v15, v140
	v_mov_b32_e32 v20, v140
	v_mov_b32_e32 v21, v140
	v_mov_b32_e32 v22, v140
	v_mov_b32_e32 v23, v140
	v_mov_b32_e32 v24, v140
	v_mov_b32_e32 v25, v140
	v_mov_b32_e32 v26, v140
	v_mov_b32_e32 v27, v140
	v_mov_b32_e32 v28, v140
	v_mov_b32_e32 v29, v140
	v_mov_b32_e32 v30, v140
	v_mov_b32_e32 v31, v140
	v_mov_b32_e32 v36, v140
	v_mov_b32_e32 v37, v140
	v_mov_b32_e32 v38, v140
	v_mov_b32_e32 v39, v140
	v_mov_b32_e32 v44, v140
	v_mov_b32_e32 v45, v140
	v_mov_b32_e32 v46, v140
	v_mov_b32_e32 v47, v140
	v_mov_b32_e32 v48, v140
	v_mov_b32_e32 v49, v140
	v_mov_b32_e32 v50, v140
	v_mov_b32_e32 v51, v140
	v_mov_b32_e32 v52, v140
	v_mov_b32_e32 v53, v140
	v_mov_b32_e32 v54, v140
	v_mov_b32_e32 v55, v140
	v_mov_b32_e32 v64, v140
	v_mov_b32_e32 v65, v140
	v_mov_b32_e32 v66, v140
	v_mov_b32_e32 v67, v140
	v_mov_b32_e32 v72, v140
	v_mov_b32_e32 v73, v140
	v_mov_b32_e32 v74, v140
	v_mov_b32_e32 v75, v140
	v_mov_b32_e32 v76, v140
	v_mov_b32_e32 v77, v140
	v_mov_b32_e32 v78, v140
	v_mov_b32_e32 v79, v140
	v_mov_b32_e32 v84, v140
	v_mov_b32_e32 v85, v140
	v_mov_b32_e32 v86, v140
	v_mov_b32_e32 v87, v140
	v_mov_b32_e32 v92, v140
	v_mov_b32_e32 v93, v140
	v_mov_b32_e32 v94, v140
	v_mov_b32_e32 v95, v140
	v_mov_b32_e32 v96, v140
	v_mov_b32_e32 v97, v140
	v_mov_b32_e32 v98, v140
	v_mov_b32_e32 v99, v140
	v_mov_b32_e32 v100, v140
	v_mov_b32_e32 v101, v140
	v_mov_b32_e32 v102, v140
	v_mov_b32_e32 v103, v140
	v_mov_b32_e32 v108, v140
	v_mov_b32_e32 v109, v140
	v_mov_b32_e32 v110, v140
	v_mov_b32_e32 v111, v140
	v_mov_b32_e32 v120, v140
	v_mov_b32_e32 v121, v140
	v_mov_b32_e32 v122, v140
	v_mov_b32_e32 v123, v140
	v_mov_b32_e32 v124, v140
	v_mov_b32_e32 v125, v140
	v_mov_b32_e32 v126, v140
	v_mov_b32_e32 v127, v140
	v_mov_b32_e32 v128, v140
	v_mov_b32_e32 v129, v140
	v_mov_b32_e32 v130, v140
	v_mov_b32_e32 v131, v140
	v_mov_b32_e32 v132, v140
	v_mov_b32_e32 v133, v140
	v_mov_b32_e32 v134, v140
	v_mov_b32_e32 v135, v140
	v_mov_b32_e32 v136, v140
	v_mov_b32_e32 v137, v140
	v_mov_b32_e32 v138, v140
	v_mov_b32_e32 v139, v140
	v_mov_b32_e32 v144, v140
	v_mov_b32_e32 v145, v140
	v_mov_b32_e32 v146, v140
	v_mov_b32_e32 v147, v140
	v_mov_b32_e32 v148, v140
	v_mov_b32_e32 v149, v140
	v_mov_b32_e32 v150, v140
	v_mov_b32_e32 v151, v140
	v_mov_b32_e32 v152, v140
	v_mov_b32_e32 v153, v140
	v_mov_b32_e32 v154, v140
	v_mov_b32_e32 v155, v140
	v_mov_b32_e32 v156, v140
	v_mov_b32_e32 v157, v140
	v_mov_b32_e32 v158, v140
	v_mov_b32_e32 v159, v140
	v_mov_b32_e32 v160, v140
	v_mov_b32_e32 v161, v140
	v_mov_b32_e32 v162, v140
	v_mov_b32_e32 v163, v140
	v_mov_b32_e32 v164, v140
	v_mov_b32_e32 v165, v140
	v_mov_b32_e32 v166, v140
	v_mov_b32_e32 v167, v140
	v_mov_b32_e32 v168, v140
	v_mov_b32_e32 v169, v140
	v_mov_b32_e32 v170, v140
	v_mov_b32_e32 v171, v140
	v_mov_b32_e32 v172, v140
	v_mov_b32_e32 v173, v140
	v_mov_b32_e32 v174, v140
	v_mov_b32_e32 v175, v140
	s_setprio 2
	v_readlane_b32 s98, v253, 3
	v_readlane_b32 s99, v253, 4
	v_and_b32_e32 v224, 15, v188
	v_bfe_u32 v225, v188, 4, 2
	v_lshrrev_b32_e32 v226, 2, v224
	v_sub_u32_e32 v226, 0, v226
	v_and_b32_e32 v226, 3, v226
	v_xor_b32_e32 v225, v225, v226
	v_lshlrev_b32_e32 v225, 4, v225
	v_lshl_or_b32 v225, v224, 6, v225
	v_bfe_u32 v226, v188, 7, 1
	v_lshl_or_b32 v185, v226, 13, v225
	v_bfe_u32 v226, v188, 6, 1
	v_lshl_or_b32 v184, v226, 12, v225
	v_add_u32_e32 v184, 0x4000, v184
	v_lshrrev_b32_e32 v224, 3, v188
	v_bfe_u32 v225, v188, 2, 1
	v_lshrrev_b32_e32 v226, 2, v224
	v_sub_u32_e32 v226, 0, v226
	v_and_b32_e32 v226, 3, v226
	v_and_b32_e32 v227, 3, v188
	v_xor_b32_e32 v226, v227, v226
	v_lshlrev_b32_e32 v226, 4, v226
	v_xor_b32_e32 v224, v224, v225
	v_lshl_or_b32 v226, v224, 6, v226
	v_mul_u32_u24_e32 v225, 0x6000, v225
	v_add_u32_e32 v183, v225, v226
	s_mov_b32 m0, 0
	s_sub_u32 vcc_lo, s6, s98
	v_add_u32_e32 v186, vcc_lo, v178
	v_add_u32_e32 v187, vcc_lo, v180
	v_add_u32_e32 v190, s26, v187
	global_load_dwordx4 v[190:193], v190, s[98:99] offset:128
	v_add_u32_e32 v194, s27, v187
	global_load_dwordx4 v[194:197], v194, s[98:99] offset:128
	v_add_u32_e32 v198, s20, v187
	global_load_dwordx4 v[198:201], v198, s[98:99] offset:128
	v_add_u32_e32 v204, s21, v187
	global_load_dwordx4 v[204:207], v204, s[98:99] offset:128
	v_add_u32_e32 v208, s56, v187
	global_load_dwordx4 v[208:211], v208, s[98:99] offset:128
	v_add_u32_e32 v212, s57, v187
	global_load_dwordx4 v[212:215], v212, s[98:99] offset:128
	v_add_u32_e32 v216, s24, v187
	global_load_dwordx4 v[216:219], v216, s[98:99] offset:128
	v_add_u32_e32 v220, s96, v187
	global_load_dwordx4 v[220:223], v220, s[98:99] offset:128
	v_mov_b32_e32 v224, v186
	global_load_dwordx4 v[224:227], v224, s[98:99] offset:128
	v_add_u32_e32 v228, s13, v186
	global_load_dwordx4 v[228:231], v228, s[98:99] offset:128
	v_add_u32_e32 v232, s12, v186
	global_load_dwordx4 v[232:235], v232, s[98:99] offset:128
	v_add_u32_e32 v236, s11, v186
	global_load_dwordx4 v[236:239], v236, s[98:99] offset:128
	s_barrier
	s_waitcnt vmcnt(12)
	ds_write_b128 v183, v[116:119]
	ds_write_b128 v183, v[112:115] offset:2048
	ds_write_b128 v183, v[104:107] offset:4096
	ds_write_b128 v183, v[88:91] offset:6144
	ds_write_b128 v183, v[80:83] offset:8192
	ds_write_b128 v183, v[68:71] offset:10240
	ds_write_b128 v183, v[60:63] offset:12288
	ds_write_b128 v183, v[40:43] offset:14336
	ds_write_b128 v183, v[56:59] offset:16384
	ds_write_b128 v183, v[32:35] offset:18432
	ds_write_b128 v183, v[16:19] offset:20480
	ds_write_b128 v183, v[8:11] offset:22528
	v_cmp_gt_u32_e32 vcc, 0x6000, v183
	v_add_u32_e32 v182, 0xc000, v183
	v_add_u32_e32 v183, 0xffffa000, v183
	s_nop 0
	v_cndmask_b32_e32 v183, v183, v182, vcc
	s_waitcnt vmcnt(0)
	v_mov_b64_e32 v[116:117], v[190:191]
	v_mov_b64_e32 v[118:119], v[192:193]
	v_mov_b64_e32 v[112:113], v[194:195]
	v_mov_b64_e32 v[114:115], v[196:197]
	v_mov_b64_e32 v[104:105], v[198:199]
	v_mov_b64_e32 v[106:107], v[200:201]
	v_mov_b64_e32 v[88:89], v[204:205]
	v_mov_b64_e32 v[90:91], v[206:207]
	v_mov_b64_e32 v[80:81], v[208:209]
	v_mov_b64_e32 v[82:83], v[210:211]
	v_mov_b64_e32 v[68:69], v[212:213]
	v_mov_b64_e32 v[70:71], v[214:215]
	v_mov_b64_e32 v[60:61], v[216:217]
	v_mov_b64_e32 v[62:63], v[218:219]
	v_mov_b64_e32 v[40:41], v[220:221]
	v_mov_b64_e32 v[42:43], v[222:223]
	v_mov_b64_e32 v[56:57], v[224:225]
	v_mov_b64_e32 v[58:59], v[226:227]
	v_mov_b64_e32 v[32:33], v[228:229]
	v_mov_b64_e32 v[34:35], v[230:231]
	v_mov_b64_e32 v[16:17], v[232:233]
	v_mov_b64_e32 v[18:19], v[234:235]
	v_mov_b64_e32 v[8:9], v[236:237]
	v_mov_b64_e32 v[10:11], v[238:239]
	s_add_u32 s6, s6, 0x80
	s_addc_u32 s7, s7, 0

.LBB0_1064:
	s_ashr_i32 s22, s52, 3
	s_lshl_b32 s31, s22, 1
	s_and_b32 s30, s22, -16
	s_and_b32 s31, s31, 14
	s_or_b32 s30, s31, s30
	s_bfe_u32 s31, s22, 0x10003
	s_or_b32 s23, s22, 63
	s_or_b32 s30, s30, s31
	s_cmpk_lt_i32 s23, 0x80
	s_cselect_b32 s22, s30, s22
	s_lshl_b32 s23, s52, 7
	s_and_b32 s23, s23, 0x380
	s_add_i32 s22, s22, s23
	s_ashr_i32 s23, s22, 31
	s_lshr_b32 s30, s23, 27
	s_add_i32 s30, s22, s30
	s_ashr_i32 s31, s30, 5
	s_andn2_b32 s30, s30, 31
	s_sub_i32 s30, s22, s30
	s_lshr_b32 s23, s23, 25
	s_add_i32 s22, s22, s23
	s_ashr_i32 s23, s30, 31
	s_lshr_b32 s23, s23, 29
	s_ashr_i32 s22, s22, 7
	s_add_i32 s23, s30, s23
	s_ashr_i32 s23, s23, 3
	s_lshl_b32 s38, s22, 2
	s_add_i32 s38, s38, s23
	s_sub_i32 s31, s31, s38
	s_lshl_b32 s42, s31, 3
	s_add_i32 s42, s42, s30
	s_lshl_b32 s22, s22, 10
	s_lshl_b32 s38, s23, 8
	s_add_i32 s38, s38, s22
	s_lshl_b32 s53, s42, 7
	s_ashr_i32 s44, s42, 3
	s_cmp_lg_u32 s44, 2
	s_cselect_b64 s[22:23], -1, 0
	s_mov_b64 s[30:31], -1
	s_and_b64 vcc, exec, s[22:23]
	s_mov_b32 s39, 0x30000
	s_cbranch_vccz .LBB0_1068
	v_mov_b32_e32 v8, v188
	s_mov_b32 s30, 0x20000
	v_ashrrev_i32_e32 v9, 3, v8
	v_lshlrev_b32_e32 v4, 4, v8
	v_and_b32_e32 v176, 0x70, v4
	v_add_u32_e32 v4, s53, v9
	v_add_u32_e32 v0, s38, v9
	v_ashrrev_i32_e32 v5, 31, v4
	v_ashrrev_i32_e32 v1, 31, v0
	v_lshlrev_b64 v[4:5], 11, v[4:5]
	v_xor_b32_e32 v10, v9, v8
	v_lshlrev_b64 v[0:1], 11, v[0:1]
	v_lshl_add_u64 v[6:7], s[2:3], 0, v[4:5]
	v_lshlrev_b32_e32 v10, 4, v10
	v_lshl_add_u64 v[2:3], s[0:1], 0, v[0:1]
	v_lshl_add_u64 v[6:7], v[6:7], 0, v[176:177]
	v_and_b32_e32 v10, 0x70, v10
	v_lshl_add_u64 v[2:3], v[2:3], 0, v[176:177]
	v_lshl_or_b32 v176, v9, 7, v10
	v_lshlrev_b32_e32 v12, 7, v8
	v_lshrrev_b32_e32 v9, 4, v8
	v_bfe_u32 v14, v8, 4, 2
	v_and_b32_e32 v15, 7, v8
	v_add_co_u32_e32 v8, vcc, s39, v6
	v_bitop3_b32 v16, v9, v15, 3 bitop3:0x6c
	s_nop 0
	v_addc_co_u32_e32 v9, vcc, 0, v7, vcc
	v_add_co_u32_e32 v10, vcc, s30, v6
	s_mov_b32 s31, 0x10000
	s_nop 0
	v_addc_co_u32_e32 v11, vcc, 0, v7, vcc
	global_load_dwordx4 v[20:23], v[8:9], off
	global_load_dwordx4 v[24:27], v[10:11], off
	v_add_co_u32_e32 v8, vcc, s31, v6
	s_mov_b32 s40, 0x70000
	s_nop 0
	v_addc_co_u32_e32 v9, vcc, 0, v7, vcc
	v_add_co_u32_e32 v10, vcc, s40, v2
	s_mov_b32 s40, 0x60000
	s_nop 0
	v_addc_co_u32_e32 v11, vcc, 0, v3, vcc
	global_load_dwordx4 v[40:43], v[8:9], off
	global_load_dwordx4 v[48:51], v[10:11], off
	v_add_co_u32_e32 v8, vcc, s40, v2
	s_mov_b32 s40, 0x50000
	s_nop 0
	v_addc_co_u32_e32 v9, vcc, 0, v3, vcc
	v_add_co_u32_e32 v10, vcc, s40, v2
	s_mov_b32 s40, 0x40000
	s_nop 0
	v_addc_co_u32_e32 v11, vcc, 0, v3, vcc
	global_load_dwordx4 v[60:63], v[8:9], off
	global_load_dwordx4 v[68:71], v[10:11], off
	v_add_co_u32_e32 v8, vcc, s40, v2
	v_and_b32_e32 v13, 0xffffc780, v12
	s_nop 0
	v_addc_co_u32_e32 v9, vcc, 0, v3, vcc
	v_add_co_u32_e32 v10, vcc, s39, v2
	v_and_b32_e32 v12, 0x2780, v12
	s_nop 0
	v_addc_co_u32_e32 v11, vcc, 0, v3, vcc
	global_load_dwordx4 v[80:83], v[8:9], off
	global_load_dwordx4 v[88:91], v[10:11], off
	v_add_co_u32_e32 v8, vcc, s30, v2
	v_bitop3_b32 v14, v14, v15, 4 bitop3:0x36
	s_nop 0
	v_addc_co_u32_e32 v9, vcc, 0, v3, vcc
	v_add_co_u32_e32 v10, vcc, s31, v2
	v_mov_b32_e32 v140, 0
	s_nop 0
	v_addc_co_u32_e32 v11, vcc, 0, v3, vcc
	global_load_dwordx4 v[104:107], v[8:9], off
	global_load_dwordx4 v[112:115], v[10:11], off
	global_load_dwordx4 v[100:103], v[6:7], off
	global_load_dwordx4 v[116:119], v[2:3], off
	v_lshlrev_b32_e32 v2, 4, v16
	v_or_b32_e32 v185, v13, v2
	v_or_b32_e32 v184, v12, v2
	v_lshlrev_b32_e32 v2, 4, v14
	v_or_b32_e32 v183, v13, v2
	v_or_b32_e32 v182, v12, v2
	v_lshlrev_b32_e32 v2, 4, v15
	v_or_b32_e32 v0, v0, v2
	v_or_b32_e32 v4, v4, v2
	v_lshl_add_u64 v[178:179], s[34:35], 0, v[0:1]
	v_lshl_add_u64 v[180:181], s[50:51], 0, v[4:5]
	s_mov_b64 s[30:31], 0
	v_mov_b32_e32 v141, v140
	v_mov_b32_e32 v142, v140
	v_mov_b32_e32 v143, v140
	v_mov_b32_e32 v0, v140
	v_mov_b32_e32 v1, v140
	v_mov_b32_e32 v2, v140
	v_mov_b32_e32 v3, v140
	v_mov_b32_e32 v4, v140
	v_mov_b32_e32 v5, v140
	v_mov_b32_e32 v6, v140
	v_mov_b32_e32 v7, v140
	v_mov_b32_e32 v8, v140
	v_mov_b32_e32 v9, v140
	v_mov_b32_e32 v10, v140
	v_mov_b32_e32 v11, v140
	v_mov_b32_e32 v12, v140
	v_mov_b32_e32 v13, v140
	v_mov_b32_e32 v14, v140
	v_mov_b32_e32 v15, v140
	v_mov_b32_e32 v16, v140
	v_mov_b32_e32 v17, v140
	v_mov_b32_e32 v18, v140
	v_mov_b32_e32 v19, v140
	v_mov_b32_e32 v28, v140
	v_mov_b32_e32 v29, v140
	v_mov_b32_e32 v30, v140
	v_mov_b32_e32 v31, v140
	v_mov_b32_e32 v32, v140
	v_mov_b32_e32 v33, v140
	v_mov_b32_e32 v34, v140
	v_mov_b32_e32 v35, v140
	v_mov_b32_e32 v36, v140
	v_mov_b32_e32 v37, v140
	v_mov_b32_e32 v38, v140
	v_mov_b32_e32 v39, v140
	v_mov_b32_e32 v44, v140
	v_mov_b32_e32 v45, v140
	v_mov_b32_e32 v46, v140
	v_mov_b32_e32 v47, v140
	v_mov_b32_e32 v52, v140
	v_mov_b32_e32 v53, v140
	v_mov_b32_e32 v54, v140
	v_mov_b32_e32 v55, v140
	v_mov_b32_e32 v56, v140
	v_mov_b32_e32 v57, v140
	v_mov_b32_e32 v58, v140
	v_mov_b32_e32 v59, v140
	v_mov_b32_e32 v64, v140
	v_mov_b32_e32 v65, v140
	v_mov_b32_e32 v66, v140
	v_mov_b32_e32 v67, v140
	v_mov_b32_e32 v72, v140
	v_mov_b32_e32 v73, v140
	v_mov_b32_e32 v74, v140
	v_mov_b32_e32 v75, v140
	v_mov_b32_e32 v76, v140
	v_mov_b32_e32 v77, v140
	v_mov_b32_e32 v78, v140
	v_mov_b32_e32 v79, v140
	v_mov_b32_e32 v84, v140
	v_mov_b32_e32 v85, v140
	v_mov_b32_e32 v86, v140
	v_mov_b32_e32 v87, v140
	v_mov_b32_e32 v92, v140
	v_mov_b32_e32 v93, v140
	v_mov_b32_e32 v94, v140
	v_mov_b32_e32 v95, v140
	v_mov_b32_e32 v96, v140
	v_mov_b32_e32 v97, v140
	v_mov_b32_e32 v98, v140
	v_mov_b32_e32 v99, v140
	v_mov_b32_e32 v108, v140
	v_mov_b32_e32 v109, v140
	v_mov_b32_e32 v110, v140
	v_mov_b32_e32 v111, v140
	v_mov_b32_e32 v120, v140
	v_mov_b32_e32 v121, v140
	v_mov_b32_e32 v122, v140
	v_mov_b32_e32 v123, v140
	v_mov_b32_e32 v124, v140
	v_mov_b32_e32 v125, v140
	v_mov_b32_e32 v126, v140
	v_mov_b32_e32 v127, v140
	v_mov_b32_e32 v128, v140
	v_mov_b32_e32 v129, v140
	v_mov_b32_e32 v130, v140
	v_mov_b32_e32 v131, v140
	v_mov_b32_e32 v132, v140
	v_mov_b32_e32 v133, v140
	v_mov_b32_e32 v134, v140
	v_mov_b32_e32 v135, v140
	v_mov_b32_e32 v136, v140
	v_mov_b32_e32 v137, v140
	v_mov_b32_e32 v138, v140
	v_mov_b32_e32 v139, v140
	v_mov_b32_e32 v144, v140
	v_mov_b32_e32 v145, v140
	v_mov_b32_e32 v146, v140
	v_mov_b32_e32 v147, v140
	v_mov_b32_e32 v148, v140
	v_mov_b32_e32 v149, v140
	v_mov_b32_e32 v150, v140
	v_mov_b32_e32 v151, v140
	v_mov_b32_e32 v152, v140
	v_mov_b32_e32 v153, v140
	v_mov_b32_e32 v154, v140
	v_mov_b32_e32 v155, v140
	v_mov_b32_e32 v156, v140
	v_mov_b32_e32 v157, v140
	v_mov_b32_e32 v158, v140
	v_mov_b32_e32 v159, v140
	v_mov_b32_e32 v160, v140
	v_mov_b32_e32 v161, v140
	v_mov_b32_e32 v162, v140
	v_mov_b32_e32 v163, v140
	v_mov_b32_e32 v164, v140
	v_mov_b32_e32 v165, v140
	v_mov_b32_e32 v166, v140
	v_mov_b32_e32 v167, v140
	v_mov_b32_e32 v168, v140
	v_mov_b32_e32 v169, v140
	v_mov_b32_e32 v170, v140
	v_mov_b32_e32 v171, v140
	v_mov_b32_e32 v172, v140
	v_mov_b32_e32 v173, v140
	v_mov_b32_e32 v174, v140
	v_mov_b32_e32 v175, v140
	s_mov_b32 s40, 0x820000
	s_mov_b32 s41, 0x830000
	s_setprio 2
	v_readlane_b32 s98, v253, 3
	v_readlane_b32 s99, v253, 4
	v_and_b32_e32 v236, 15, v188
	v_bfe_u32 v237, v188, 4, 2
	v_lshrrev_b32_e32 v238, 2, v236
	v_sub_u32_e32 v238, 0, v238
	v_and_b32_e32 v238, 3, v238
	v_xor_b32_e32 v237, v237, v238
	v_lshlrev_b32_e32 v237, 4, v237
	v_lshl_or_b32 v237, v236, 6, v237
	v_bfe_u32 v238, v188, 7, 1
	v_lshl_or_b32 v185, v238, 13, v237
	v_bfe_u32 v238, v188, 6, 1
	v_lshl_or_b32 v184, v238, 12, v237
	v_add_u32_e32 v184, 0x4000, v184
	v_lshrrev_b32_e32 v236, 3, v188
	v_bfe_u32 v237, v188, 2, 1
	v_lshrrev_b32_e32 v238, 2, v236
	v_sub_u32_e32 v238, 0, v238
	v_and_b32_e32 v238, 3, v238
	v_and_b32_e32 v239, 3, v188
	v_xor_b32_e32 v238, v239, v238
	v_lshlrev_b32_e32 v238, 4, v238
	v_xor_b32_e32 v236, v236, v237
	v_lshl_or_b32 v238, v236, 6, v238
	v_mul_u32_u24_e32 v237, 0x6000, v237
	v_add_u32_e32 v183, v237, v238
	s_mov_b32 m0, 0
	s_sub_u32 vcc_lo, s30, s98
	v_add_u32_e32 v186, vcc_lo, v178
	v_add_u32_e32 v187, vcc_lo, v180
	v_add_u32_e32 v204, s26, v186
	global_load_dwordx4 v[204:207], v204, s[98:99] offset:128
	v_add_u32_e32 v208, s27, v186
	global_load_dwordx4 v[208:211], v208, s[98:99] offset:128
	v_add_u32_e32 v212, s20, v186
	global_load_dwordx4 v[212:215], v212, s[98:99] offset:128
	v_add_u32_e32 v216, s21, v186
	global_load_dwordx4 v[216:219], v216, s[98:99] offset:128
	v_add_u32_e32 v220, s56, v186
	global_load_dwordx4 v[220:223], v220, s[98:99] offset:128
	v_add_u32_e32 v224, s57, v186
	global_load_dwordx4 v[224:227], v224, s[98:99] offset:128
	v_add_u32_e32 v228, s24, v186
	global_load_dwordx4 v[228:231], v228, s[98:99] offset:128
	v_add_u32_e32 v232, s96, v186
	global_load_dwordx4 v[232:235], v232, s[98:99] offset:128
	v_add_u32_e32 v236, s25, v187
	global_load_dwordx4 v[236:239], v236, s[98:99] offset:128
	v_add_u32_e32 v240, s33, v187
	global_load_dwordx4 v[240:243], v240, s[98:99] offset:128
	v_add_u32_e32 v244, s40, v187
	global_load_dwordx4 v[244:247], v244, s[98:99] offset:128
	v_add_u32_e32 v248, s41, v187
	global_load_dwordx4 v[248:251], v248, s[98:99] offset:128
	s_barrier
	s_waitcnt vmcnt(12)
	ds_write_b128 v183, v[116:119]
	ds_write_b128 v183, v[112:115] offset:2048
	ds_write_b128 v183, v[104:107] offset:4096
	ds_write_b128 v183, v[88:91] offset:6144
	ds_write_b128 v183, v[80:83] offset:8192
	ds_write_b128 v183, v[68:71] offset:10240
	ds_write_b128 v183, v[60:63] offset:12288
	ds_write_b128 v183, v[48:51] offset:14336
	ds_write_b128 v183, v[100:103] offset:16384
	ds_write_b128 v183, v[40:43] offset:18432
	ds_write_b128 v183, v[24:27] offset:20480
	ds_write_b128 v183, v[20:23] offset:22528
	v_cmp_gt_u32_e32 vcc, 0x6000, v183
	v_add_u32_e32 v182, 0xc000, v183
	v_add_u32_e32 v183, 0xffffa000, v183
	s_nop 0
	v_cndmask_b32_e32 v183, v183, v182, vcc
	s_waitcnt vmcnt(0)
	v_mov_b64_e32 v[116:117], v[204:205]
	v_mov_b64_e32 v[118:119], v[206:207]
	v_mov_b64_e32 v[112:113], v[208:209]
	v_mov_b64_e32 v[114:115], v[210:211]
	v_mov_b64_e32 v[104:105], v[212:213]
	v_mov_b64_e32 v[106:107], v[214:215]
	v_mov_b64_e32 v[88:89], v[216:217]
	v_mov_b64_e32 v[90:91], v[218:219]
	v_mov_b64_e32 v[80:81], v[220:221]
	v_mov_b64_e32 v[82:83], v[222:223]
	v_mov_b64_e32 v[68:69], v[224:225]
	v_mov_b64_e32 v[70:71], v[226:227]
	v_mov_b64_e32 v[60:61], v[228:229]
	v_mov_b64_e32 v[62:63], v[230:231]
	v_mov_b64_e32 v[48:49], v[232:233]
	v_mov_b64_e32 v[50:51], v[234:235]
	v_mov_b64_e32 v[100:101], v[236:237]
	v_mov_b64_e32 v[102:103], v[238:239]
	v_mov_b64_e32 v[40:41], v[240:241]
	v_mov_b64_e32 v[42:43], v[242:243]
	v_mov_b64_e32 v[24:25], v[244:245]
	v_mov_b64_e32 v[26:27], v[246:247]
	v_mov_b64_e32 v[20:21], v[248:249]
	v_mov_b64_e32 v[22:23], v[250:251]
	s_add_u32 s30, s30, 0x80
	s_addc_u32 s31, s31, 0

.LBB0_1068:
	s_and_b64 vcc, exec, s[30:31]
	s_cbranch_vccz .LBB0_1072
	s_nop 2
	v_mov_b32_e32 v8, v188
	s_mov_b32 s30, 0x20000
	v_ashrrev_i32_e32 v9, 3, v8
	v_lshlrev_b32_e32 v4, 4, v8
	v_and_b32_e32 v176, 0x70, v4
	v_add_u32_e32 v4, s53, v9
	v_add_u32_e32 v0, s38, v9
	v_ashrrev_i32_e32 v5, 31, v4
	v_ashrrev_i32_e32 v1, 31, v0
	v_lshlrev_b64 v[4:5], 11, v[4:5]
	v_xor_b32_e32 v10, v9, v8
	v_lshlrev_b64 v[0:1], 11, v[0:1]
	v_lshl_add_u64 v[6:7], s[2:3], 0, v[4:5]
	v_lshlrev_b32_e32 v10, 4, v10
	v_lshl_add_u64 v[2:3], s[0:1], 0, v[0:1]
	v_lshl_add_u64 v[6:7], v[6:7], 0, v[176:177]
	v_and_b32_e32 v10, 0x70, v10
	v_lshl_add_u64 v[2:3], v[2:3], 0, v[176:177]
	v_lshl_or_b32 v176, v9, 7, v10
	v_lshlrev_b32_e32 v12, 7, v8
	v_lshrrev_b32_e32 v9, 4, v8
	v_bfe_u32 v14, v8, 4, 2
	v_and_b32_e32 v15, 7, v8
	v_add_co_u32_e32 v8, vcc, s39, v6
	v_bitop3_b32 v16, v9, v15, 3 bitop3:0x6c
	s_nop 0
	v_addc_co_u32_e32 v9, vcc, 0, v7, vcc
	v_add_co_u32_e32 v10, vcc, s30, v6
	s_mov_b32 s31, 0x10000
	s_nop 0
	v_addc_co_u32_e32 v11, vcc, 0, v7, vcc
	global_load_dwordx4 v[20:23], v[8:9], off
	global_load_dwordx4 v[24:27], v[10:11], off
	v_add_co_u32_e32 v8, vcc, s31, v6
	s_mov_b32 s40, 0x70000
	s_nop 0
	v_addc_co_u32_e32 v9, vcc, 0, v7, vcc
	v_add_co_u32_e32 v10, vcc, s40, v2
	s_mov_b32 s40, 0x60000
	s_nop 0
	v_addc_co_u32_e32 v11, vcc, 0, v3, vcc
	global_load_dwordx4 v[40:43], v[8:9], off
	global_load_dwordx4 v[48:51], v[10:11], off
	v_add_co_u32_e32 v8, vcc, s40, v2
	s_mov_b32 s40, 0x50000
	s_nop 0
	v_addc_co_u32_e32 v9, vcc, 0, v3, vcc
	v_add_co_u32_e32 v10, vcc, s40, v2
	s_mov_b32 s40, 0x40000
	s_nop 0
	v_addc_co_u32_e32 v11, vcc, 0, v3, vcc
	global_load_dwordx4 v[60:63], v[8:9], off
	global_load_dwordx4 v[68:71], v[10:11], off
	v_add_co_u32_e32 v8, vcc, s40, v2
	v_and_b32_e32 v13, 0xffffc780, v12
	s_nop 0
	v_addc_co_u32_e32 v9, vcc, 0, v3, vcc
	v_add_co_u32_e32 v10, vcc, s39, v2
	v_and_b32_e32 v12, 0x2780, v12
	s_nop 0
	v_addc_co_u32_e32 v11, vcc, 0, v3, vcc
	global_load_dwordx4 v[80:83], v[8:9], off
	global_load_dwordx4 v[88:91], v[10:11], off
	v_add_co_u32_e32 v8, vcc, s30, v2
	v_bitop3_b32 v14, v14, v15, 4 bitop3:0x36
	s_nop 0
	v_addc_co_u32_e32 v9, vcc, 0, v3, vcc
	v_add_co_u32_e32 v10, vcc, s31, v2
	v_mov_b32_e32 v140, 0
	s_nop 0
	v_addc_co_u32_e32 v11, vcc, 0, v3, vcc
	global_load_dwordx4 v[104:107], v[8:9], off
	global_load_dwordx4 v[112:115], v[10:11], off
	global_load_dwordx4 v[100:103], v[6:7], off
	global_load_dwordx4 v[116:119], v[2:3], off
	v_lshlrev_b32_e32 v2, 4, v16
	v_or_b32_e32 v185, v13, v2
	v_or_b32_e32 v184, v12, v2
	v_lshlrev_b32_e32 v2, 4, v14
	v_or_b32_e32 v183, v13, v2
	v_or_b32_e32 v182, v12, v2
	v_lshlrev_b32_e32 v2, 4, v15
	v_or_b32_e32 v0, v0, v2
	v_or_b32_e32 v4, v4, v2
	v_lshl_add_u64 v[178:179], s[34:35], 0, v[0:1]
	v_lshl_add_u64 v[180:181], s[50:51], 0, v[4:5]
	s_mov_b64 s[30:31], 0
	v_mov_b32_e32 v141, v140
	v_mov_b32_e32 v142, v140
	v_mov_b32_e32 v143, v140
	v_mov_b32_e32 v0, v140
	v_mov_b32_e32 v1, v140
	v_mov_b32_e32 v2, v140
	v_mov_b32_e32 v3, v140
	v_mov_b32_e32 v4, v140
	v_mov_b32_e32 v5, v140
	v_mov_b32_e32 v6, v140
	v_mov_b32_e32 v7, v140
	v_mov_b32_e32 v8, v140
	v_mov_b32_e32 v9, v140
	v_mov_b32_e32 v10, v140
	v_mov_b32_e32 v11, v140
	v_mov_b32_e32 v12, v140
	v_mov_b32_e32 v13, v140
	v_mov_b32_e32 v14, v140
	v_mov_b32_e32 v15, v140
	v_mov_b32_e32 v16, v140
	v_mov_b32_e32 v17, v140
	v_mov_b32_e32 v18, v140
	v_mov_b32_e32 v19, v140
	v_mov_b32_e32 v28, v140
	v_mov_b32_e32 v29, v140
	v_mov_b32_e32 v30, v140
	v_mov_b32_e32 v31, v140
	v_mov_b32_e32 v32, v140
	v_mov_b32_e32 v33, v140
	v_mov_b32_e32 v34, v140
	v_mov_b32_e32 v35, v140
	v_mov_b32_e32 v36, v140
	v_mov_b32_e32 v37, v140
	v_mov_b32_e32 v38, v140
	v_mov_b32_e32 v39, v140
	v_mov_b32_e32 v44, v140
	v_mov_b32_e32 v45, v140
	v_mov_b32_e32 v46, v140
	v_mov_b32_e32 v47, v140
	v_mov_b32_e32 v52, v140
	v_mov_b32_e32 v53, v140
	v_mov_b32_e32 v54, v140
	v_mov_b32_e32 v55, v140
	v_mov_b32_e32 v56, v140
	v_mov_b32_e32 v57, v140
	v_mov_b32_e32 v58, v140
	v_mov_b32_e32 v59, v140
	v_mov_b32_e32 v64, v140
	v_mov_b32_e32 v65, v140
	v_mov_b32_e32 v66, v140
	v_mov_b32_e32 v67, v140
	v_mov_b32_e32 v72, v140
	v_mov_b32_e32 v73, v140
	v_mov_b32_e32 v74, v140
	v_mov_b32_e32 v75, v140
	v_mov_b32_e32 v76, v140
	v_mov_b32_e32 v77, v140
	v_mov_b32_e32 v78, v140
	v_mov_b32_e32 v79, v140
	v_mov_b32_e32 v84, v140
	v_mov_b32_e32 v85, v140
	v_mov_b32_e32 v86, v140
	v_mov_b32_e32 v87, v140
	v_mov_b32_e32 v92, v140
	v_mov_b32_e32 v93, v140
	v_mov_b32_e32 v94, v140
	v_mov_b32_e32 v95, v140
	v_mov_b32_e32 v96, v140
	v_mov_b32_e32 v97, v140
	v_mov_b32_e32 v98, v140
	v_mov_b32_e32 v99, v140
	v_mov_b32_e32 v108, v140
	v_mov_b32_e32 v109, v140
	v_mov_b32_e32 v110, v140
	v_mov_b32_e32 v111, v140
	v_mov_b32_e32 v120, v140
	v_mov_b32_e32 v121, v140
	v_mov_b32_e32 v122, v140
	v_mov_b32_e32 v123, v140
	v_mov_b32_e32 v124, v140
	v_mov_b32_e32 v125, v140
	v_mov_b32_e32 v126, v140
	v_mov_b32_e32 v127, v140
	v_mov_b32_e32 v128, v140
	v_mov_b32_e32 v129, v140
	v_mov_b32_e32 v130, v140
	v_mov_b32_e32 v131, v140
	v_mov_b32_e32 v132, v140
	v_mov_b32_e32 v133, v140
	v_mov_b32_e32 v134, v140
	v_mov_b32_e32 v135, v140
	v_mov_b32_e32 v136, v140
	v_mov_b32_e32 v137, v140
	v_mov_b32_e32 v138, v140
	v_mov_b32_e32 v139, v140
	v_mov_b32_e32 v144, v140
	v_mov_b32_e32 v145, v140
	v_mov_b32_e32 v146, v140
	v_mov_b32_e32 v147, v140
	v_mov_b32_e32 v148, v140
	v_mov_b32_e32 v149, v140
	v_mov_b32_e32 v150, v140
	v_mov_b32_e32 v151, v140
	v_mov_b32_e32 v152, v140
	v_mov_b32_e32 v153, v140
	v_mov_b32_e32 v154, v140
	v_mov_b32_e32 v155, v140
	v_mov_b32_e32 v156, v140
	v_mov_b32_e32 v157, v140
	v_mov_b32_e32 v158, v140
	v_mov_b32_e32 v159, v140
	v_mov_b32_e32 v160, v140
	v_mov_b32_e32 v161, v140
	v_mov_b32_e32 v162, v140
	v_mov_b32_e32 v163, v140
	v_mov_b32_e32 v164, v140
	v_mov_b32_e32 v165, v140
	v_mov_b32_e32 v166, v140
	v_mov_b32_e32 v167, v140
	v_mov_b32_e32 v168, v140
	v_mov_b32_e32 v169, v140
	v_mov_b32_e32 v170, v140
	v_mov_b32_e32 v171, v140
	v_mov_b32_e32 v172, v140
	v_mov_b32_e32 v173, v140
	v_mov_b32_e32 v174, v140
	v_mov_b32_e32 v175, v140
	s_mov_b32 s39, 0x820000
	s_mov_b32 s40, 0x830000
	s_setprio 2
	v_readlane_b32 s98, v253, 3
	v_readlane_b32 s99, v253, 4
	v_and_b32_e32 v240, 15, v188
	v_bfe_u32 v241, v188, 4, 2
	v_lshrrev_b32_e32 v242, 2, v240
	v_sub_u32_e32 v242, 0, v242
	v_and_b32_e32 v242, 3, v242
	v_xor_b32_e32 v241, v241, v242
	v_lshlrev_b32_e32 v241, 4, v241
	v_lshl_or_b32 v241, v240, 6, v241
	v_bfe_u32 v242, v188, 7, 1
	v_lshl_or_b32 v185, v242, 13, v241
	v_bfe_u32 v242, v188, 6, 1
	v_lshl_or_b32 v184, v242, 12, v241
	v_add_u32_e32 v184, 0x4000, v184
	v_lshrrev_b32_e32 v240, 3, v188
	v_bfe_u32 v241, v188, 2, 1
	v_lshrrev_b32_e32 v242, 2, v240
	v_sub_u32_e32 v242, 0, v242
	v_and_b32_e32 v242, 3, v242
	v_and_b32_e32 v243, 3, v188
	v_xor_b32_e32 v242, v243, v242
	v_lshlrev_b32_e32 v242, 4, v242
	v_xor_b32_e32 v240, v240, v241
	v_lshl_or_b32 v242, v240, 6, v242
	v_mul_u32_u24_e32 v241, 0x6000, v241
	v_add_u32_e32 v183, v241, v242
	s_mov_b32 m0, 0
	s_sub_u32 vcc_lo, s30, s98
	v_add_u32_e32 v186, vcc_lo, v178
	v_add_u32_e32 v187, vcc_lo, v180
	v_add_u32_e32 v208, s26, v186
	global_load_dwordx4 v[208:211], v208, s[98:99] offset:128
	v_add_u32_e32 v212, s27, v186
	global_load_dwordx4 v[212:215], v212, s[98:99] offset:128
	v_add_u32_e32 v216, s20, v186
	global_load_dwordx4 v[216:219], v216, s[98:99] offset:128
	v_add_u32_e32 v220, s21, v186
	global_load_dwordx4 v[220:223], v220, s[98:99] offset:128
	v_add_u32_e32 v224, s56, v186
	global_load_dwordx4 v[224:227], v224, s[98:99] offset:128
	v_add_u32_e32 v228, s57, v186
	global_load_dwordx4 v[228:231], v228, s[98:99] offset:128
	v_add_u32_e32 v232, s24, v186
	global_load_dwordx4 v[232:235], v232, s[98:99] offset:128
	v_add_u32_e32 v236, s96, v186
	global_load_dwordx4 v[236:239], v236, s[98:99] offset:128
	v_add_u32_e32 v240, s25, v187
	global_load_dwordx4 v[240:243], v240, s[98:99] offset:128
	v_add_u32_e32 v244, s33, v187
	global_load_dwordx4 v[244:247], v244, s[98:99] offset:128
	v_add_u32_e32 v248, s39, v187
	global_load_dwordx4 v[248:251], v248, s[98:99] offset:128
	v_add_u32_e32 v204, s40, v187
	global_load_dwordx4 v[204:207], v204, s[98:99] offset:128
	s_barrier
	s_waitcnt vmcnt(12)
	ds_write_b128 v183, v[116:119]
	ds_write_b128 v183, v[112:115] offset:2048
	ds_write_b128 v183, v[104:107] offset:4096
	ds_write_b128 v183, v[88:91] offset:6144
	ds_write_b128 v183, v[80:83] offset:8192
	ds_write_b128 v183, v[68:71] offset:10240
	ds_write_b128 v183, v[60:63] offset:12288
	ds_write_b128 v183, v[48:51] offset:14336
	ds_write_b128 v183, v[100:103] offset:16384
	ds_write_b128 v183, v[40:43] offset:18432
	ds_write_b128 v183, v[24:27] offset:20480
	ds_write_b128 v183, v[20:23] offset:22528
	v_cmp_gt_u32_e32 vcc, 0x6000, v183
	v_add_u32_e32 v182, 0xc000, v183
	v_add_u32_e32 v183, 0xffffa000, v183
	s_nop 0
	v_cndmask_b32_e32 v183, v183, v182, vcc
	s_waitcnt vmcnt(0)
	v_mov_b64_e32 v[116:117], v[208:209]
	v_mov_b64_e32 v[118:119], v[210:211]
	v_mov_b64_e32 v[112:113], v[212:213]
	v_mov_b64_e32 v[114:115], v[214:215]
	v_mov_b64_e32 v[104:105], v[216:217]
	v_mov_b64_e32 v[106:107], v[218:219]
	v_mov_b64_e32 v[88:89], v[220:221]
	v_mov_b64_e32 v[90:91], v[222:223]
	v_mov_b64_e32 v[80:81], v[224:225]
	v_mov_b64_e32 v[82:83], v[226:227]
	v_mov_b64_e32 v[68:69], v[228:229]
	v_mov_b64_e32 v[70:71], v[230:231]
	v_mov_b64_e32 v[60:61], v[232:233]
	v_mov_b64_e32 v[62:63], v[234:235]
	v_mov_b64_e32 v[48:49], v[236:237]
	v_mov_b64_e32 v[50:51], v[238:239]
	v_mov_b64_e32 v[100:101], v[240:241]
	v_mov_b64_e32 v[102:103], v[242:243]
	v_mov_b64_e32 v[40:41], v[244:245]
	v_mov_b64_e32 v[42:43], v[246:247]
	v_mov_b64_e32 v[24:25], v[248:249]
	v_mov_b64_e32 v[26:27], v[250:251]
	v_mov_b64_e32 v[20:21], v[204:205]
	v_mov_b64_e32 v[22:23], v[206:207]
	s_add_u32 s30, s30, 0x80
	s_addc_u32 s31, s31, 0
